# NA and ret_out output stores widened the same way (v_permlane16_swap tile pairs, 8B stores become 16B stores), on top of the widened ret_kv stores
# speedup vs baseline: 1.0099x; 1.0052x over previous
; #define LAS __attribute__((address_space(3)))
; DI unsigned pk2(float lo, float hi) { return pg8::cvt_pk_bf16(lo, hi); }
; DI int lbid() { int b = (int)blockIdx.x; asm volatile("" : "+s"(b)); return b; }
; DI int lgdim() { int g = (int)gridDim.x; asm volatile("" : "+s"(g)); return g; }
; DI void ret_out_phase(const Params& P, LAS unsigned char* lds, int r, const bf16* QKV, const bf16* ST, bf16* CAT) {
;     ...
;     for (int u = lbid(); u < 128 * NTH; u += lgdim()) {
;         int g = g0, li = li0; asm volatile("" : "+v"(g), "+v"(li));
;         const int n = u / NTH, h = u % NTH;
;         const int tokbase = n * 128, pos0 = (n % cps) * 128;
;         const float l2f = ret_log2gamma(P, 0, h), l2b = ret_log2gamma(P, 1, h);
;         const bf16* stf = ST + ((size_t)(0 * 128 + n) * NTH + h) * 16384; const bf16* stb = ST + ((size_t)(1 * 128 + n) * NTH + h) * 16384;
;         _Pragma("unroll") for (int it_ = 0; it_ < 4; ++it_) { const int task = tid + 512 * it_; const int which = task >> 10, j = (task >> 3) & 127, dg = task & 7;
;             const bf16* kp = QKV + (size_t)(tokbase + j) * NIN0 + which * 1536 + h * 128 + dg * 8;
;             const bf16x8 lo = __builtin_nontemporal_load((const bf16x8*)kp), hi = __builtin_nontemporal_load((const bf16x8*)(kp + 64));
;             const float* cp = rc + (size_t)(pos0 + j) * 64 + dg * 8; const float* sp = rsn + (size_t)(pos0 + j) * 64 + dg * 8;
;             const f32x4 c0 = *(const f32x4*)cp, c1 = *(const f32x4*)(cp + 4), s0 = *(const f32x4*)sp, s1 = *(const f32x4*)(sp + 4);
;             const float w = which ? QK_SCALE : 1.0f;
;             float o1[8], o2[8];
; #pragma unroll
;             for (int e = 0; e < 8; ++e) { const float x1 = bf2f((unsigned short)lo[e]), x2 = bf2f((unsigned short)hi[e]); const float c = e < 4 ? c0[e & 3] : c1[e & 3], sn = e < 4 ? s0[e & 3] : s1[e & 3];
;                 o1[e] = (x1 * c - x2 * sn) * w; o2[e] = (x1 * sn + x2 * c) * w; }
;             v4u a, b;
;             a.x = pk2(o1[0], o1[1]); a.y = pk2(o1[2], o1[3]); a.z = pk2(o1[4], o1[5]); a.w = pk2(o1[6], o1[7]);
;             b.x = pk2(o2[0], o2[1]); b.y = pk2(o2[2], o2[3]); b.z = pk2(o2[4], o2[5]); b.w = pk2(o2[6], o2[7]);
;             LAS unsigned char* dst = which ? RB : RA;
;             *(LAS v4u*)(dst + j * PITCH + dg * 16) = a; *(LAS v4u*)(dst + j * PITCH + 128 + dg * 16) = b; }
.LBB0_180:
	s_mul_hi_i32 s0, s20, 0x2aaaaaab
	s_lshr_b32 s1, s0, 31
	s_ashr_i32 s3, s0, 1
	s_add_i32 s3, s3, s1
	s_abs_i32 s4, s3
	s_mul_hi_u32 s5, s4, s23
	s_mul_i32 s5, s5, s21
	s_mul_i32 s2, s3, 12
	s_sub_i32 s4, s4, s5
	s_sub_i32 s6, s20, s2
	s_lshl_b32 s0, s3, 7
	s_ashr_i32 s1, s3, 31
	s_sub_i32 s5, s4, s21
	s_cmp_ge_u32 s4, s21
	s_cselect_b32 s4, s5, s4
	s_sub_i32 s5, s4, s21
	s_cmp_ge_u32 s4, s21
	s_cselect_b32 s4, s5, s4
	s_xor_b32 s4, s4, s1
	s_sub_i32 s1, s4, s1
	s_ashr_i32 s7, s6, 31
	s_lshl_b32 s1, s1, 7
	s_lshl_b64 s[4:5], s[6:7], 2
	s_add_u32 s18, s50, s4
	s_addc_u32 s19, s51, s5
	s_mul_hi_i32 s4, s3, 12
	s_add_u32 s8, s2, s6
	s_addc_u32 s9, s4, s7
	s_addk_i32 s3, 0x80
	v_or_b32_e32 v0, s1, v109
	s_addk_i32 s2, 0x600
	s_mul_hi_i32 s3, s3, 12
	v_ashrrev_i32_e32 v1, 31, v0
	s_add_u32 s4, s2, s6
	v_lshlrev_b64 v[0:1], 8, v[0:1]
	s_addc_u32 s5, s3, s7
	s_lshl_b32 s2, s6, 7
	v_or_b32_e32 v32, s0, v109
	v_lshl_add_u64 v[24:25], v[48:49], 0, v[0:1]
	v_lshl_add_u64 v[26:27], v[50:51], 0, v[0:1]
	s_ashr_i32 s3, s2, 31
	v_mad_i64_i32 v[0:1], s[6:7], v32, s29, v[56:57]
	s_lshl_b64 s[6:7], s[2:3], 1
	s_nop 0
	v_lshl_add_u64 v[8:9], v[0:1], 0, s[6:7]
	v_mov_b32_e32 v28, v104
	v_mov_b32_e32 v29, v105
	v_lshl_add_u64 v[12:13], v[8:9], 0, v[128:129]
	flat_load_dwordx4 v[16:19], v[26:27]
	flat_load_dwordx4 v[20:23], v[24:25]
	flat_load_dwordx4 v[0:3], v[26:27] offset:16
	flat_load_dwordx4 v[4:7], v[24:25] offset:16
	flat_load_dwordx4 v[8:11], v[12:13] nt
	s_nop 0
	flat_load_dwordx4 v[12:15], v[12:13] offset:128 nt
	v_mov_b64_e32 v[34:35], s[18:19]
	flat_load_dword v30, v[34:35]
	flat_load_dword v31, v[34:35] offset:48
	v_mov_b32_e32 v81, v129
	v_add_u32_e32 v137, s22, v29
	s_waitcnt vmcnt(0) lgkmcnt(0)
	v_mov_b32_e32 v37, v16
	v_mov_b32_e32 v36, v20
	v_mov_b32_e32 v38, v18
	v_mov_b32_e32 v39, v22
	v_mov_b32_e32 v40, v22
	v_mov_b32_e32 v41, v18
	v_mov_b32_e32 v22, v19
	v_mov_b32_e32 v18, v23
	v_mov_b32_e32 v42, v0
	v_mov_b32_e32 v43, v4
	v_lshlrev_b32_e32 v47, 16, v8
	v_lshlrev_b32_e32 v46, 16, v12
	v_and_b32_e32 v83, 0xffff0000, v8
	v_and_b32_e32 v82, 0xffff0000, v12
	v_lshlrev_b32_e32 v85, 16, v9
	v_lshlrev_b32_e32 v84, 16, v13
	v_and_b32_e32 v9, 0xffff0000, v9
	v_and_b32_e32 v8, 0xffff0000, v13
	v_lshlrev_b32_e32 v13, 16, v10
	v_lshlrev_b32_e32 v12, 16, v14
	v_mov_b32_e32 v34, v16
	v_mov_b32_e32 v35, v20
	v_pk_mul_f32 v[36:37], v[36:37], v[46:47]
	v_pk_mul_f32 v[22:23], v[22:23], v[8:9]
	v_pk_mul_f32 v[8:9], v[18:19], v[8:9]
	v_pk_mul_f32 v[18:19], v[42:43], v[12:13]
	v_mov_b32_e32 v44, v4
	v_pk_mul_f32 v[34:35], v[34:35], v[46:47]
	v_add_f32_e32 v33, v36, v37
	v_add_f32_e32 v8, v8, v9
	v_sub_f32_e32 v9, v19, v18
	v_mov_b32_e32 v45, v0
	v_sub_f32_e32 v4, v35, v34
	v_sub_f32_e32 v22, v23, v22
	v_mul_f32_e32 v19, v110, v33
	v_mul_f32_e32 v23, v110, v8
	v_mul_f32_e32 v33, v110, v9
	v_pk_mul_f32 v[8:9], v[44:45], v[12:13]
	v_mul_f32_e32 v18, v110, v4
	v_add_f32_e32 v0, v8, v9
	v_and_b32_e32 v9, 0xffff0000, v10
	v_and_b32_e32 v8, 0xffff0000, v14
	v_mov_b32_e32 v4, v1
	v_pk_mul_f32 v[12:13], v[4:5], v[8:9]
	v_mul_f32_e32 v34, v110, v0
	v_sub_f32_e32 v0, v13, v12
	v_mul_f32_e32 v10, v110, v0
	v_mov_b32_e32 v0, v5
	v_pk_mul_f32 v[0:1], v[0:1], v[8:9]
	v_mov_b32_e32 v4, v2
	v_add_f32_e32 v0, v0, v1
	v_mul_f32_e32 v8, v110, v0
	v_lshlrev_b32_e32 v1, 16, v11
	v_lshlrev_b32_e32 v0, 16, v15
	v_mov_b32_e32 v5, v6
	v_pk_mul_f32 v[4:5], v[4:5], v[0:1]
	v_mov_b32_e32 v20, v17
	v_sub_f32_e32 v4, v5, v4
	v_mul_f32_e32 v9, v110, v4
	v_mov_b32_e32 v4, v6
	v_mov_b32_e32 v5, v2
	v_pk_mul_f32 v[0:1], v[4:5], v[0:1]
	v_mov_b32_e32 v6, v3
	v_add_f32_e32 v0, v0, v1
	v_mul_f32_e32 v12, v110, v0
	v_and_b32_e32 v1, 0xffff0000, v11
	v_and_b32_e32 v0, 0xffff0000, v15
	v_pk_mul_f32 v[4:5], v[6:7], v[0:1]
	v_mov_b32_e32 v16, v21
	v_sub_f32_e32 v2, v5, v4
	v_mul_f32_e32 v4, v110, v2
	v_mov_b32_e32 v2, v7
	v_pk_mul_f32 v[20:21], v[20:21], v[82:83]
	v_pk_mul_f32 v[16:17], v[16:17], v[82:83]
	v_pk_mul_f32 v[38:39], v[38:39], v[84:85]
	v_pk_mul_f32 v[0:1], v[2:3], v[0:1]
	v_pk_mul_f32 v[40:41], v[40:41], v[84:85]
	v_sub_f32_e32 v20, v21, v20
	v_add_f32_e32 v16, v16, v17
	v_sub_f32_e32 v17, v39, v38
	v_add_f32_e32 v0, v0, v1
	v_add_f32_e32 v21, v40, v41
	v_mul_f32_e32 v20, v110, v20
	v_mul_f32_e32 v17, v110, v17
	v_mul_f32_e32 v22, v110, v22
	v_mul_f32_e32 v7, v110, v0
	v_cvt_pk_bf16_f32 v0, v18, v20
	v_cvt_pk_bf16_f32 v1, v17, v22
	v_cvt_pk_bf16_f32 v2, v33, v10
	v_cvt_pk_bf16_f32 v3, v9, v4
	v_mul_f32_e32 v16, v110, v16
	v_mul_f32_e32 v21, v110, v21
	v_cvt_pk_bf16_f32 v4, v19, v16
	v_cvt_pk_bf16_f32 v5, v21, v23
	v_cvt_pk_bf16_f32 v6, v34, v8
	v_cvt_pk_bf16_f32 v7, v12, v7
	ds_write_b128 v127, v[0:3]
	ds_write_b128 v127, v[4:7] offset:128
	v_or_b32_e32 v0, s0, v111
	v_mad_i64_i32 v[0:1], s[2:3], v0, s29, v[58:59]
	v_lshl_add_u64 v[0:1], v[0:1], 0, s[6:7]
	v_or_b32_e32 v8, s1, v111
	v_lshl_add_u64 v[4:5], v[0:1], 0, v[128:129]
	v_ashrrev_i32_e32 v9, 31, v8
	flat_load_dwordx4 v[0:3], v[4:5] nt
	s_nop 0
	flat_load_dwordx4 v[4:7], v[4:5] offset:128 nt
	v_lshlrev_b64 v[8:9], 8, v[8:9]
	v_lshl_add_u64 v[20:21], v[48:49], 0, v[8:9]
	v_lshl_add_u64 v[16:17], v[50:51], 0, v[8:9]
	flat_load_dwordx4 v[8:11], v[16:17]
	flat_load_dwordx4 v[12:15], v[20:21]
	s_nop 0
	flat_load_dwordx4 v[16:19], v[16:17] offset:16
	s_nop 0
	flat_load_dwordx4 v[20:23], v[20:21] offset:16
	v_add_u32_e32 v84, s0, v137
	s_waitcnt vmcnt(0) lgkmcnt(0)
; #define LAS __attribute__((address_space(3)))
; DI unsigned pk2(float lo, float hi) { return pg8::cvt_pk_bf16(lo, hi); }
; DI void ret_out_phase(const Params& P, LAS unsigned char* lds, int r, const bf16* QKV, const bf16* ST, bf16* CAT) {
;     ...
;         _Pragma("unroll") for (int it_ = 0; it_ < 4; ++it_) { const int task = tid + 512 * it_; const int which = task >> 10, j = (task >> 3) & 127, dg = task & 7;
;             const bf16* kp = QKV + (size_t)(tokbase + j) * NIN0 + which * 1536 + h * 128 + dg * 8;
;             const bf16x8 lo = __builtin_nontemporal_load((const bf16x8*)kp), hi = __builtin_nontemporal_load((const bf16x8*)(kp + 64));
;             const float* cp = rc + (size_t)(pos0 + j) * 64 + dg * 8; const float* sp = rsn + (size_t)(pos0 + j) * 64 + dg * 8;
;             const f32x4 c0 = *(const f32x4*)cp, c1 = *(const f32x4*)(cp + 4), s0 = *(const f32x4*)sp, s1 = *(const f32x4*)(sp + 4);
;             const float w = which ? QK_SCALE : 1.0f;
;             float o1[8], o2[8];
; #pragma unroll
;             for (int e = 0; e < 8; ++e) { const float x1 = bf2f((unsigned short)lo[e]), x2 = bf2f((unsigned short)hi[e]); const float c = e < 4 ? c0[e & 3] : c1[e & 3], sn = e < 4 ? s0[e & 3] : s1[e & 3];
;                 o1[e] = (x1 * c - x2 * sn) * w; o2[e] = (x1 * sn + x2 * c) * w; }
;             v4u a, b;
;             a.x = pk2(o1[0], o1[1]); a.y = pk2(o1[2], o1[3]); a.z = pk2(o1[4], o1[5]); a.w = pk2(o1[6], o1[7]);
;             b.x = pk2(o2[0], o2[1]); b.y = pk2(o2[2], o2[3]); b.z = pk2(o2[4], o2[5]); b.w = pk2(o2[6], o2[7]);
;             LAS unsigned char* dst = which ? RB : RA;
;             *(LAS v4u*)(dst + j * PITCH + dg * 16) = a; *(LAS v4u*)(dst + j * PITCH + 128 + dg * 16) = b; }
	v_and_b32_e32 v41, 0xffff0000, v0
	v_and_b32_e32 v40, 0xffff0000, v4
	v_mov_b32_e32 v36, v8
	v_mov_b32_e32 v39, v8
	v_mov_b32_e32 v8, v13
	v_lshlrev_b32_e32 v35, 16, v0
	v_lshlrev_b32_e32 v34, 16, v4
	v_mov_b32_e32 v37, v12
	v_mov_b32_e32 v38, v12
	v_mov_b32_e32 v12, v9
	v_pk_mul_f32 v[8:9], v[8:9], v[40:41]
	v_pk_mul_f32 v[36:37], v[36:37], v[34:35]
	v_pk_mul_f32 v[34:35], v[38:39], v[34:35]
	v_add_f32_e32 v8, v8, v9
	v_lshlrev_b32_e32 v43, 16, v1
	v_lshlrev_b32_e32 v42, 16, v5
	v_add_f32_e32 v4, v34, v35
	v_mul_f32_e32 v34, v112, v8
	v_mov_b32_e32 v8, v10
	v_mov_b32_e32 v9, v14
	v_pk_mul_f32 v[12:13], v[12:13], v[40:41]
	v_sub_f32_e32 v0, v37, v36
	v_pk_mul_f32 v[8:9], v[8:9], v[42:43]
	v_sub_f32_e32 v12, v13, v12
	v_mul_f32_e32 v13, v112, v0
	v_sub_f32_e32 v0, v9, v8
	v_mov_b32_e32 v8, v14
	v_mov_b32_e32 v9, v10
	v_pk_mul_f32 v[8:9], v[8:9], v[42:43]
	v_mul_f32_e32 v35, v112, v0
	v_add_f32_e32 v0, v8, v9
	v_mul_f32_e32 v8, v112, v0
	v_and_b32_e32 v1, 0xffff0000, v1
	v_and_b32_e32 v0, 0xffff0000, v5
	v_mov_b32_e32 v14, v11
	v_mov_b32_e32 v10, v15
	v_mul_f32_e32 v33, v112, v4
	v_pk_mul_f32 v[4:5], v[14:15], v[0:1]
	v_pk_mul_f32 v[0:1], v[10:11], v[0:1]
	v_sub_f32_e32 v4, v5, v4
	v_add_f32_e32 v0, v0, v1
	v_mul_f32_e32 v9, v112, v4
	v_mul_f32_e32 v10, v112, v0
	v_lshlrev_b32_e32 v1, 16, v2
	v_lshlrev_b32_e32 v0, 16, v6
	v_mov_b32_e32 v4, v16
	v_mov_b32_e32 v5, v20
	v_pk_mul_f32 v[4:5], v[4:5], v[0:1]
	v_mul_f32_e32 v12, v112, v12
	v_sub_f32_e32 v4, v5, v4
	v_mul_f32_e32 v11, v112, v4
	v_mov_b32_e32 v4, v20
	v_mov_b32_e32 v5, v16
	v_pk_mul_f32 v[0:1], v[4:5], v[0:1]
	v_mov_b32_e32 v20, v17
	v_add_f32_e32 v0, v0, v1
	v_mul_f32_e32 v14, v112, v0
	v_and_b32_e32 v1, 0xffff0000, v2
	v_and_b32_e32 v0, 0xffff0000, v6
	v_mov_b32_e32 v16, v21
	v_pk_mul_f32 v[4:5], v[20:21], v[0:1]
	v_pk_mul_f32 v[0:1], v[16:17], v[0:1]
	v_sub_f32_e32 v2, v5, v4
	v_add_f32_e32 v0, v0, v1
	v_mul_f32_e32 v15, v112, v0
	v_lshlrev_b32_e32 v1, 16, v3
	v_lshlrev_b32_e32 v0, 16, v7
	v_mov_b32_e32 v4, v18
	v_mov_b32_e32 v5, v22
	v_pk_mul_f32 v[4:5], v[4:5], v[0:1]
	v_mul_f32_e32 v6, v112, v2
	v_sub_f32_e32 v2, v5, v4
	v_mov_b32_e32 v4, v22
	v_mov_b32_e32 v5, v18
	v_pk_mul_f32 v[0:1], v[4:5], v[0:1]
	v_mov_b32_e32 v22, v19
	v_add_f32_e32 v0, v0, v1
	v_mul_f32_e32 v17, v112, v0
	v_and_b32_e32 v1, 0xffff0000, v3
	v_and_b32_e32 v0, 0xffff0000, v7
	v_mul_f32_e32 v16, v112, v2
	v_pk_mul_f32 v[2:3], v[22:23], v[0:1]
	v_mov_b32_e32 v18, v23
	v_sub_f32_e32 v2, v3, v2
	v_pk_mul_f32 v[0:1], v[18:19], v[0:1]
	v_mul_f32_e32 v3, v112, v2
	v_add_f32_e32 v0, v0, v1
	v_mul_f32_e32 v7, v112, v0
	v_cvt_pk_bf16_f32 v0, v13, v12
	v_cvt_pk_bf16_f32 v1, v35, v9
	v_cvt_pk_bf16_f32 v2, v11, v6
	v_cvt_pk_bf16_f32 v3, v16, v3
	v_cvt_pk_bf16_f32 v4, v33, v34
	v_cvt_pk_bf16_f32 v5, v8, v10
	v_cvt_pk_bf16_f32 v6, v14, v15
	v_cvt_pk_bf16_f32 v7, v17, v7
	ds_write_b128 v132, v[0:3]
	ds_write_b128 v132, v[4:7] offset:128
	v_mad_i64_i32 v[0:1], s[2:3], v32, s29, v[60:61]
	v_lshl_add_u64 v[0:1], v[0:1], 0, s[6:7]
	v_lshl_add_u64 v[4:5], v[0:1], 0, v[128:129]
	flat_load_dwordx4 v[0:3], v[4:5] nt
	s_nop 0
	flat_load_dwordx4 v[4:7], v[4:5] offset:128 nt
	s_nop 0
	flat_load_dwordx4 v[8:11], v[26:27]
	flat_load_dwordx4 v[12:15], v[24:25]
	flat_load_dwordx4 v[16:19], v[26:27] offset:16
	flat_load_dwordx4 v[20:23], v[24:25] offset:16
	s_waitcnt vmcnt(0) lgkmcnt(0)
	v_lshlrev_b32_e32 v25, 16, v0
	v_lshlrev_b32_e32 v24, 16, v4
	v_mov_b32_e32 v26, v8
	v_mov_b32_e32 v27, v12
	v_pk_mul_f32 v[26:27], v[26:27], v[24:25]
	s_nop 0
	v_sub_f32_e32 v26, v27, v26
	v_mul_f32_e32 v32, v113, v26
	v_mov_b32_e32 v26, v12
	v_mov_b32_e32 v27, v8
	v_pk_mul_f32 v[24:25], v[26:27], v[24:25]
	v_mov_b32_e32 v12, v9
	v_add_f32_e32 v8, v24, v25
	v_and_b32_e32 v25, 0xffff0000, v0
	v_and_b32_e32 v24, 0xffff0000, v4
	v_mul_f32_e32 v33, v113, v8
	v_pk_mul_f32 v[26:27], v[12:13], v[24:25]
	v_mov_b32_e32 v8, v13
	v_sub_f32_e32 v0, v27, v26
	v_pk_mul_f32 v[8:9], v[8:9], v[24:25]
	v_mul_f32_e32 v26, v113, v0
	v_add_f32_e32 v0, v8, v9
	v_lshlrev_b32_e32 v9, 16, v1
	v_lshlrev_b32_e32 v8, 16, v5
	v_mov_b32_e32 v12, v10
	v_mov_b32_e32 v13, v14
	v_pk_mul_f32 v[12:13], v[12:13], v[8:9]
	v_mul_f32_e32 v24, v113, v0
	v_sub_f32_e32 v0, v13, v12
	v_mov_b32_e32 v12, v14
	v_mov_b32_e32 v13, v10
	v_pk_mul_f32 v[8:9], v[12:13], v[8:9]
	v_mul_f32_e32 v25, v113, v0
	v_add_f32_e32 v0, v8, v9
	v_mul_f32_e32 v8, v113, v0
	v_and_b32_e32 v1, 0xffff0000, v1
	v_and_b32_e32 v0, 0xffff0000, v5
	v_mov_b32_e32 v14, v11
	v_mov_b32_e32 v10, v15
	v_pk_mul_f32 v[4:5], v[14:15], v[0:1]
	v_pk_mul_f32 v[0:1], v[10:11], v[0:1]
	v_sub_f32_e32 v4, v5, v4
	v_add_f32_e32 v0, v0, v1
	v_mul_f32_e32 v9, v113, v4
	v_mul_f32_e32 v10, v113, v0
	v_lshlrev_b32_e32 v1, 16, v2
	v_lshlrev_b32_e32 v0, 16, v6
	v_mov_b32_e32 v4, v16
	v_mov_b32_e32 v5, v20
	v_pk_mul_f32 v[4:5], v[4:5], v[0:1]
	s_nop 0
	v_sub_f32_e32 v4, v5, v4
	v_mul_f32_e32 v11, v113, v4
	v_mov_b32_e32 v4, v20
	v_mov_b32_e32 v5, v16
	v_pk_mul_f32 v[0:1], v[4:5], v[0:1]
	v_mov_b32_e32 v20, v17
	v_add_f32_e32 v0, v0, v1
	v_mul_f32_e32 v12, v113, v0
	v_and_b32_e32 v1, 0xffff0000, v2
	v_and_b32_e32 v0, 0xffff0000, v6
	v_mov_b32_e32 v16, v21
	v_pk_mul_f32 v[4:5], v[20:21], v[0:1]
	v_pk_mul_f32 v[0:1], v[16:17], v[0:1]
	v_sub_f32_e32 v2, v5, v4
	v_add_f32_e32 v0, v0, v1
	v_mul_f32_e32 v13, v113, v0
	v_lshlrev_b32_e32 v1, 16, v3
	v_lshlrev_b32_e32 v0, 16, v7
	v_mov_b32_e32 v4, v18
	v_mov_b32_e32 v5, v22
	v_pk_mul_f32 v[4:5], v[4:5], v[0:1]
	v_mul_f32_e32 v6, v113, v2
	v_sub_f32_e32 v2, v5, v4
	v_mov_b32_e32 v4, v22
	v_mov_b32_e32 v5, v18
	v_pk_mul_f32 v[0:1], v[4:5], v[0:1]
	v_mov_b32_e32 v22, v19
	v_add_f32_e32 v0, v0, v1
	v_mul_f32_e32 v15, v113, v0
	v_and_b32_e32 v1, 0xffff0000, v3
	v_and_b32_e32 v0, 0xffff0000, v7
	v_mul_f32_e32 v14, v113, v2
	v_pk_mul_f32 v[2:3], v[22:23], v[0:1]
	v_mov_b32_e32 v18, v23
	v_sub_f32_e32 v2, v3, v2
	v_pk_mul_f32 v[0:1], v[18:19], v[0:1]
	v_mul_f32_e32 v3, v113, v2
	v_add_f32_e32 v0, v0, v1
	v_mul_f32_e32 v7, v113, v0
	v_cvt_pk_bf16_f32 v0, v32, v26
	v_cvt_pk_bf16_f32 v1, v25, v9
	v_cvt_pk_bf16_f32 v2, v11, v6
	v_cvt_pk_bf16_f32 v3, v14, v3
	v_cvt_pk_bf16_f32 v4, v33, v24
	v_cvt_pk_bf16_f32 v5, v8, v10
	v_cvt_pk_bf16_f32 v6, v12, v13
	v_cvt_pk_bf16_f32 v7, v15, v7
	ds_write_b128 v133, v[0:3]
	ds_write_b128 v133, v[4:7] offset:128
	v_or_b32_e32 v0, s0, v114
	v_mad_i64_i32 v[0:1], s[2:3], v0, s29, v[62:63]
	v_lshl_add_u64 v[0:1], v[0:1], 0, s[6:7]
	v_or_b32_e32 v8, s1, v114
	v_lshl_add_u64 v[4:5], v[0:1], 0, v[128:129]
	v_ashrrev_i32_e32 v9, 31, v8
	flat_load_dwordx4 v[0:3], v[4:5] nt
	s_nop 0
	flat_load_dwordx4 v[4:7], v[4:5] offset:128 nt
	v_lshlrev_b64 v[8:9], 8, v[8:9]
	v_lshl_add_u64 v[20:21], v[48:49], 0, v[8:9]
	v_lshl_add_u64 v[16:17], v[50:51], 0, v[8:9]
	flat_load_dwordx4 v[8:11], v[16:17]
	flat_load_dwordx4 v[12:15], v[20:21]
	s_nop 0
	flat_load_dwordx4 v[16:19], v[16:17] offset:16
	s_nop 0
	flat_load_dwordx4 v[20:23], v[20:21] offset:16
	s_waitcnt vmcnt(0) lgkmcnt(0)
; #define LAS __attribute__((address_space(3)))
; DI unsigned pk2(float lo, float hi) { return pg8::cvt_pk_bf16(lo, hi); }
; DI float fexp2(float x) { return __builtin_amdgcn_exp2f(x); }
; DI void ret_out_phase(const Params& P, LAS unsigned char* lds, int r, const bf16* QKV, const bf16* ST, bf16* CAT) {
;     ...
;         _Pragma("unroll") for (int it_ = 0; it_ < 4; ++it_) { const int task = tid + 512 * it_; const int which = task >> 10, j = (task >> 3) & 127, dg = task & 7;
;             const bf16* kp = QKV + (size_t)(tokbase + j) * NIN0 + which * 1536 + h * 128 + dg * 8;
;             const bf16x8 lo = __builtin_nontemporal_load((const bf16x8*)kp), hi = __builtin_nontemporal_load((const bf16x8*)(kp + 64));
;             const float* cp = rc + (size_t)(pos0 + j) * 64 + dg * 8; const float* sp = rsn + (size_t)(pos0 + j) * 64 + dg * 8;
;             const f32x4 c0 = *(const f32x4*)cp, c1 = *(const f32x4*)(cp + 4), s0 = *(const f32x4*)sp, s1 = *(const f32x4*)(sp + 4);
;             const float w = which ? QK_SCALE : 1.0f;
;             float o1[8], o2[8];
; #pragma unroll
;             for (int e = 0; e < 8; ++e) { const float x1 = bf2f((unsigned short)lo[e]), x2 = bf2f((unsigned short)hi[e]); const float c = e < 4 ? c0[e & 3] : c1[e & 3], sn = e < 4 ? s0[e & 3] : s1[e & 3];
;                 o1[e] = (x1 * c - x2 * sn) * w; o2[e] = (x1 * sn + x2 * c) * w; }
;             v4u a, b;
;             a.x = pk2(o1[0], o1[1]); a.y = pk2(o1[2], o1[3]); a.z = pk2(o1[4], o1[5]); a.w = pk2(o1[6], o1[7]);
;             b.x = pk2(o2[0], o2[1]); b.y = pk2(o2[2], o2[3]); b.z = pk2(o2[4], o2[5]); b.w = pk2(o2[6], o2[7]);
;             LAS unsigned char* dst = which ? RB : RA;
;             *(LAS v4u*)(dst + j * PITCH + dg * 16) = a; *(LAS v4u*)(dst + j * PITCH + 128 + dg * 16) = b; }
;         _Pragma("unroll") for (int it_ = 0; it_ < 4; ++it_) { const int task = tid + 512 * it_; const int j = task >> 4, c = task & 15;
;             *(LAS v4u*)(RC + j * PITCH + c * 16) = __builtin_nontemporal_load((const v4u*)(QKV + (size_t)(tokbase + j) * NIN0 + 3072 + h * 128 + c * 8));
;             *(LAS v4u*)(RD + j * PITCH + c * 16) = __builtin_nontemporal_load((const v4u*)(stf + j * 128 + c * 8)); }
;     ...
;                 for (int i = 0; i < 4; ++i) { const int dd = itok - (16 * t + 4 * g + i);
;                     sacc[t][i] *= dd >= 0 ? fexp2((float)dd * l2f) : fexp2((float)(-dd) * l2b); }
	v_lshlrev_b32_e32 v25, 16, v0
	v_lshlrev_b32_e32 v24, 16, v4
	v_mov_b32_e32 v26, v8
	v_mov_b32_e32 v27, v12
	v_pk_mul_f32 v[26:27], v[26:27], v[24:25]
	s_nop 0
	v_sub_f32_e32 v26, v27, v26
	v_mul_f32_e32 v32, v115, v26
	v_mov_b32_e32 v26, v12
	v_mov_b32_e32 v27, v8
	v_pk_mul_f32 v[24:25], v[26:27], v[24:25]
	v_mov_b32_e32 v12, v9
	v_add_f32_e32 v8, v24, v25
	v_and_b32_e32 v25, 0xffff0000, v0
	v_and_b32_e32 v24, 0xffff0000, v4
	v_mul_f32_e32 v33, v115, v8
	v_pk_mul_f32 v[26:27], v[12:13], v[24:25]
	v_mov_b32_e32 v8, v13
	v_sub_f32_e32 v0, v27, v26
	v_pk_mul_f32 v[8:9], v[8:9], v[24:25]
	v_mul_f32_e32 v26, v115, v0
	v_add_f32_e32 v0, v8, v9
	v_lshlrev_b32_e32 v9, 16, v1
	v_lshlrev_b32_e32 v8, 16, v5
	v_mov_b32_e32 v12, v10
	v_mov_b32_e32 v13, v14
	v_pk_mul_f32 v[12:13], v[12:13], v[8:9]
	v_mul_f32_e32 v24, v115, v0
	v_sub_f32_e32 v0, v13, v12
	v_mov_b32_e32 v12, v14
	v_mov_b32_e32 v13, v10
	v_pk_mul_f32 v[8:9], v[12:13], v[8:9]
	v_mul_f32_e32 v25, v115, v0
	v_add_f32_e32 v0, v8, v9
	v_mul_f32_e32 v8, v115, v0
	v_and_b32_e32 v1, 0xffff0000, v1
	v_and_b32_e32 v0, 0xffff0000, v5
	v_mov_b32_e32 v14, v11
	v_mov_b32_e32 v10, v15
	v_pk_mul_f32 v[4:5], v[14:15], v[0:1]
	v_pk_mul_f32 v[0:1], v[10:11], v[0:1]
	v_sub_f32_e32 v4, v5, v4
	v_add_f32_e32 v0, v0, v1
	v_mul_f32_e32 v9, v115, v4
	v_mul_f32_e32 v10, v115, v0
	v_lshlrev_b32_e32 v1, 16, v2
	v_lshlrev_b32_e32 v0, 16, v6
	v_mov_b32_e32 v4, v16
	v_mov_b32_e32 v5, v20
	v_pk_mul_f32 v[4:5], v[4:5], v[0:1]
	s_nop 0
	v_sub_f32_e32 v4, v5, v4
	v_mul_f32_e32 v11, v115, v4
	v_mov_b32_e32 v4, v20
	v_mov_b32_e32 v5, v16
	v_pk_mul_f32 v[0:1], v[4:5], v[0:1]
	v_mov_b32_e32 v20, v17
	v_add_f32_e32 v0, v0, v1
	v_mul_f32_e32 v12, v115, v0
	v_and_b32_e32 v1, 0xffff0000, v2
	v_and_b32_e32 v0, 0xffff0000, v6
	v_mov_b32_e32 v16, v21
	v_pk_mul_f32 v[4:5], v[20:21], v[0:1]
	v_pk_mul_f32 v[0:1], v[16:17], v[0:1]
	v_sub_f32_e32 v2, v5, v4
	v_add_f32_e32 v0, v0, v1
	v_mul_f32_e32 v13, v115, v0
	v_lshlrev_b32_e32 v1, 16, v3
	v_lshlrev_b32_e32 v0, 16, v7
	v_mov_b32_e32 v4, v18
	v_mov_b32_e32 v5, v22
	v_pk_mul_f32 v[4:5], v[4:5], v[0:1]
	v_mul_f32_e32 v6, v115, v2
	v_sub_f32_e32 v2, v5, v4
	v_mov_b32_e32 v4, v22
	v_mov_b32_e32 v5, v18
	v_pk_mul_f32 v[0:1], v[4:5], v[0:1]
	v_mov_b32_e32 v22, v19
	v_add_f32_e32 v0, v0, v1
	v_mul_f32_e32 v15, v115, v0
	v_and_b32_e32 v1, 0xffff0000, v3
	v_and_b32_e32 v0, 0xffff0000, v7
	v_mov_b32_e32 v18, v23
	v_mul_f32_e32 v14, v115, v2
	v_pk_mul_f32 v[2:3], v[22:23], v[0:1]
	v_pk_mul_f32 v[0:1], v[18:19], v[0:1]
	v_sub_f32_e32 v2, v3, v2
	v_add_f32_e32 v0, v0, v1
	v_mul_f32_e32 v3, v115, v2
	v_mul_f32_e32 v7, v115, v0
	v_cvt_pk_bf16_f32 v0, v32, v26
	v_cvt_pk_bf16_f32 v1, v25, v9
	v_cvt_pk_bf16_f32 v2, v11, v6
	v_cvt_pk_bf16_f32 v3, v14, v3
	v_cvt_pk_bf16_f32 v4, v33, v24
	v_cvt_pk_bf16_f32 v5, v8, v10
	v_cvt_pk_bf16_f32 v6, v12, v13
	v_cvt_pk_bf16_f32 v7, v15, v7
	ds_write_b128 v134, v[0:3]
	ds_write_b128 v134, v[4:7] offset:128
	v_add_u32_e32 v0, s0, v116
	v_mov_b64_e32 v[6:7], s[44:45]
	v_mad_i64_i32 v[0:1], s[2:3], v0, s29, v[6:7]
	v_lshl_add_u64 v[0:1], v[0:1], 0, s[6:7]
	v_lshl_add_u64 v[0:1], v[0:1], 0, v[80:81]
	v_add_co_u32_e32 v0, vcc, s40, v0
	s_lshl_b64 s[2:3], s[8:9], 15
	s_nop 0
	v_addc_co_u32_e32 v1, vcc, 0, v1, vcc
	flat_load_dwordx4 v[0:3], v[0:1] offset:2048 nt
	v_lshl_add_u64 v[4:5], v[52:53], 0, s[2:3]
	v_add_u32_e32 v8, v106, v117
	v_add_u32_e32 v10, v107, v117
	v_add_u32_e32 v18, s0, v120
	v_add_u32_e32 v19, s0, v122
	v_add_u32_e32 v15, v107, v119
	v_add_u32_e32 v13, v106, v121
	v_add_u32_e32 v12, v107, v121
	v_add_u32_e32 v11, v106, v123
	s_mov_b64 s[8:9], 0x2400
	s_waitcnt vmcnt(0) lgkmcnt(0)
	ds_write_b128 v8, v[0:3]
	v_lshl_add_u64 v[0:1], v[64:65], 1, v[4:5]
	flat_load_dwordx4 v[0:3], v[0:1] nt
	v_add_u32_e32 v8, s0, v118
	v_mad_i64_i32 v[8:9], s[2:3], v8, s29, v[6:7]
	v_lshl_add_u64 v[8:9], v[8:9], 0, s[6:7]
	v_lshl_add_u64 v[8:9], v[8:9], 0, v[80:81]
	v_add_co_u32_e32 v8, vcc, s40, v8
	v_mad_i64_i32 v[32:33], s[0:1], v84, s29, v[6:7]
	s_nop 0
	v_addc_co_u32_e32 v9, vcc, 0, v9, vcc
	v_lshl_add_u64 v[32:33], v[32:33], 0, s[6:7]
	s_waitcnt vmcnt(0) lgkmcnt(0)
	ds_write_b128 v10, v[0:3]
	flat_load_dwordx4 v[0:3], v[8:9] offset:2048 nt
	v_add_u32_e32 v10, v106, v119
	v_lshl_add_u64 v[8:9], v[66:67], 1, v[4:5]
	s_waitcnt vmcnt(0) lgkmcnt(0)
	ds_write_b128 v10, v[0:3]
	flat_load_dwordx4 v[0:3], v[8:9] nt
	v_lshlrev_b32_e32 v8, 2, v28
	v_ashrrev_i32_e32 v9, 31, v8
	v_sub_u32_e32 v36, v137, v8
	v_xad_u32 v14, v8, -1, v137
	v_or_b32_e32 v16, 2, v8
	v_or_b32_e32 v17, 3, v8
	v_lshlrev_b64 v[82:83], 1, v[8:9]
	v_mad_i64_i32 v[8:9], s[0:1], v18, s29, v[6:7]
	v_lshl_add_u64 v[8:9], v[8:9], 0, s[6:7]
	v_lshl_add_u64 v[8:9], v[8:9], 0, v[80:81]
	v_add_co_u32_e32 v8, vcc, s40, v8
	v_sub_u32_e32 v34, 0, v14
	s_nop 0
	v_addc_co_u32_e32 v9, vcc, 0, v9, vcc
	v_subrev_u32_e32 v20, 17, v36
	v_sub_u32_e32 v35, 17, v36
	v_subrev_u32_e32 v21, 18, v36
	v_sub_u32_e32 v37, 18, v36
	v_subrev_u32_e32 v22, 19, v36
	v_sub_u32_e32 v38, 19, v36
	v_subrev_u32_e32 v23, 32, v36
	v_sub_u32_e32 v39, 32, v36
	v_subrev_u32_e32 v24, 33, v36
	v_sub_u32_e32 v40, 33, v36
	v_subrev_u32_e32 v25, 34, v36
	v_sub_u32_e32 v41, 34, v36
	v_subrev_u32_e32 v26, 35, v36
	v_sub_u32_e32 v42, 35, v36
	v_subrev_u32_e32 v27, 48, v36
	v_sub_u32_e32 v43, 48, v36
	v_subrev_u32_e32 v28, 49, v36
	v_sub_u32_e32 v44, 49, v36
	v_sub_u32_e32 v29, 0, v36
	v_subrev_u32_e32 v85, 50, v36
	v_sub_u32_e32 v45, 50, v36
	v_subrev_u32_e32 v86, 51, v36
	v_sub_u32_e32 v46, 51, v36
	v_subrev_u32_e32 v87, 64, v36
	v_sub_u32_e32 v47, 64, v36
	v_max_i32_e32 v150, v87, v47
	v_add_u32_e32 v10, v107, v123
	v_sub_u32_e32 v18, 16, v36
	s_waitcnt vmcnt(0) lgkmcnt(0)
; #define LAS __attribute__((address_space(3)))
; DI float ret_log2gamma(const Params& P, int dir, int h) { const float de = P.ret_decay[dir * NTH + h]; return log1pf(-exp2f(-de)) * LOG2E; }
; DI void ret_out_phase(const Params& P, LAS unsigned char* lds, int r, const bf16* QKV, const bf16* ST, bf16* CAT) {
;     ...
;         _Pragma("unroll") for (int it_ = 0; it_ < 4; ++it_) { const int task = tid + 512 * it_; const int j = task >> 4, c = task & 15;
;             *(LAS v4u*)(RC + j * PITCH + c * 16) = __builtin_nontemporal_load((const v4u*)(QKV + (size_t)(tokbase + j) * NIN0 + 3072 + h * 128 + c * 8));
;             *(LAS v4u*)(RD + j * PITCH + c * 16) = __builtin_nontemporal_load((const v4u*)(stf + j * 128 + c * 8)); }
	ds_write_b128 v15, v[0:3]
	flat_load_dwordx4 v[0:3], v[8:9] offset:2048 nt
	v_sub_u32_e32 v8, v137, v16
	v_sub_u32_e32 v9, v137, v17
	v_mad_i64_i32 v[16:17], s[0:1], v19, s29, v[6:7]
	v_max_i32_e32 v7, v14, v34
	v_max_i32_e32 v34, v20, v35
	v_max_i32_e32 v35, v21, v37
	v_max_i32_e32 v37, v22, v38
	v_max_i32_e32 v38, v23, v39
	v_max_i32_e32 v39, v24, v40
	v_cvt_f32_u32_e32 v206, v38
	v_cvt_f32_u32_e32 v207, v39
	v_lshl_add_u64 v[38:39], v[68:69], 1, v[4:5]
	v_max_i32_e32 v40, v25, v41
	v_max_i32_e32 v41, v26, v42
	v_max_i32_e32 v42, v27, v43
	v_max_i32_e32 v43, v28, v44
	v_cvt_f32_u32_e32 v204, v34
	v_cvt_f32_u32_e32 v205, v35
	v_lshl_add_u64 v[34:35], v[16:17], 0, s[6:7]
	v_cvt_f32_u32_e32 v210, v42
	v_cvt_f32_u32_e32 v211, v43
	v_lshl_add_u64 v[42:43], v[34:35], 0, v[80:81]
	v_cvt_f32_u32_e32 v208, v40
	v_cvt_f32_u32_e32 v209, v41
	v_lshl_add_u64 v[40:41], v[70:71], 1, v[4:5]
	v_max_i32_e32 v6, v36, v29
	v_sub_u32_e32 v29, 0, v9
	s_lshl_b64 s[0:1], s[4:5], 15
	v_cmp_lt_f32_e64 s[4:5], s25, v31
	v_cvt_f32_u32_e32 v151, v7
	v_max_i32_e32 v7, v9, v29
	v_cndmask_b32_e64 v29, 0, v166, s[4:5]
	v_sub_f32_e32 v29, v29, v31
	v_exp_f32_e32 v29, v29
	v_cndmask_b32_e64 v31, 0, v167, s[4:5]
	v_max_i32_e32 v44, v85, v45
	v_max_i32_e32 v45, v86, v46
	v_ldexp_f32 v29, v29, v31
	v_cvt_f32_u32_e32 v212, v44
	v_cvt_f32_u32_e32 v213, v45
	v_sub_f32_e32 v44, 1.0, v29
	v_add_f32_e32 v47, -1.0, v44
	v_frexp_mant_f32_e32 v88, v44
	v_add_u32_e32 v15, -16, v36
	v_sub_u32_e32 v19, 0, v8
	v_max_i32_e32 v18, v15, v18
	v_cvt_f32_u32_e32 v103, v6
	v_max_i32_e32 v6, v8, v19
	v_cvt_f32_u32_e32 v171, v18
	v_lshl_add_u64 v[18:19], v[54:55], 0, s[0:1]
	v_cvt_f32_u32_e32 v214, v6
	v_cvt_f32_u32_e32 v37, v37
	v_cvt_f32_u32_e32 v215, v7
	v_lshl_add_u64 v[4:5], v[72:73], 1, v[18:19]
	v_lshl_add_u64 v[6:7], v[74:75], 1, v[18:19]
	v_lshl_add_u64 v[16:17], v[76:77], 1, v[18:19]
	v_lshl_add_u64 v[18:19], v[78:79], 1, v[18:19]
	v_lshl_add_u64 v[34:35], v[32:33], 0, v[82:83]
	v_lshl_add_u64 v[32:33], v[34:35], 0, s[8:9]
	s_waitcnt vmcnt(0) lgkmcnt(0)
	ds_write_b128 v13, v[0:3]
	flat_load_dwordx4 v[0:3], v[38:39] nt
	v_add_co_u32_e32 v38, vcc, s40, v42
	s_waitcnt vmcnt(0) lgkmcnt(0)
	ds_write_b128 v12, v[0:3]
	v_addc_co_u32_e32 v39, vcc, 0, v43, vcc
	flat_load_dwordx4 v[0:3], v[38:39] offset:2048 nt
	v_cmp_lt_f32_e32 vcc, s25, v30
	v_cvt_f64_f32_e32 v[42:43], v44
	v_frexp_exp_i32_f64_e32 v42, v[42:43]
	v_cndmask_b32_e32 v13, 0, v166, vcc
	v_sub_f32_e32 v13, v13, v30
	v_exp_f32_e32 v13, v13
	v_cndmask_b32_e32 v30, 0, v167, vcc
	v_ldexp_f32 v81, v13, v30
	v_sub_f32_e32 v13, 1.0, v81
	v_frexp_mant_f32_e32 v46, v13
	v_cvt_f64_f32_e32 v[30:31], v13
	v_add_f32_e32 v45, -1.0, v13
	v_frexp_exp_i32_f64_e32 v30, v[30:31]
	v_cmp_gt_f32_e32 vcc, s26, v46
	v_sub_f32_e32 v89, v45, v13
	v_sub_f32_e64 v45, -v81, v45
	v_subbrev_co_u32_e32 v30, vcc, 0, v30, vcc
	v_sub_f32_e32 v31, v47, v44
	v_add_f32_e32 v43, 1.0, v89
	v_cmp_gt_f32_e32 vcc, s26, v88
	v_sub_f32_e64 v47, -v29, v47
	v_add_f32_e32 v31, 1.0, v31
	v_subbrev_co_u32_e32 v42, vcc, 0, v42, vcc
	v_add_f32_e32 v43, v45, v43
	v_sub_u32_e32 v45, 0, v30
	v_add_f32_e32 v31, v47, v31
	v_sub_u32_e32 v46, 0, v42
	v_ldexp_f32 v13, v13, v45
	v_ldexp_f32 v44, v44, v46
	v_ldexp_f32 v31, v31, v46
	v_add_f32_e32 v46, -1.0, v13
	v_add_f32_e32 v47, 1.0, v13
	v_ldexp_f32 v43, v43, v45
	v_add_f32_e32 v88, -1.0, v44
	v_add_f32_e32 v89, 1.0, v44
	v_add_f32_e32 v45, 1.0, v46
	v_add_f32_e32 v90, -1.0, v47
	v_add_f32_e32 v91, 1.0, v88
	v_add_f32_e32 v92, -1.0, v89
	v_sub_f32_e32 v45, v13, v45
	v_sub_f32_e32 v13, v13, v90
	v_sub_f32_e32 v90, v44, v91
	v_sub_f32_e32 v44, v44, v92
	v_add_f32_e32 v91, v43, v45
	v_add_f32_e32 v43, v43, v13
	v_add_f32_e32 v90, v31, v90
	v_add_f32_e32 v31, v31, v44
	v_add_f32_e32 v92, v47, v43
	v_add_f32_e32 v93, v89, v31
	v_rcp_f32_e32 v94, v92
	v_rcp_f32_e32 v95, v93
	v_add_f32_e32 v13, v46, v91
	v_add_f32_e32 v45, v88, v90
	v_mul_f32_e32 v98, v13, v94
	v_sub_f32_e32 v44, v92, v47
	v_sub_f32_e32 v46, v13, v46
	v_sub_f32_e32 v88, v45, v88
	v_mul_f32_e32 v99, v45, v95
	v_mul_f32_e32 v38, v92, v98
	v_sub_f32_e32 v47, v93, v89
	v_sub_f32_e32 v43, v43, v44
	v_sub_f32_e32 v96, v91, v46
	v_sub_f32_e32 v97, v90, v88
	v_mul_f32_e32 v46, v93, v99
	v_fma_f32 v88, v98, v92, -v38
	v_sub_f32_e32 v31, v31, v47
	v_fma_f32 v90, v99, v93, -v46
	v_fmac_f32_e32 v88, v98, v43
	v_fmac_f32_e32 v90, v99, v31
	v_add_f32_e32 v12, v38, v88
	v_add_f32_e32 v44, v46, v90
	v_sub_f32_e32 v39, v13, v12
	v_mov_b32_e32 v89, v12
	v_sub_f32_e32 v47, v45, v44
	v_pk_add_f32 v[12:13], v[12:13], v[38:39] neg_lo:[0,1] neg_hi:[0,1]
	s_waitcnt vmcnt(0) lgkmcnt(0)
; DI float ret_log2gamma(const Params& P, int dir, int h) { const float de = P.ret_decay[dir * NTH + h]; return log1pf(-exp2f(-de)) * LOG2E; }
; DI void ret_out_phase(const Params& P, LAS unsigned char* lds, int r, const bf16* QKV, const bf16* ST, bf16* CAT) {
;     ...
;         __syncthreads();
	ds_write_b128 v11, v[0:3]
	flat_load_dwordx4 v[0:3], v[40:41] nt
	v_mov_b32_e32 v91, v44
	v_pk_add_f32 v[44:45], v[44:45], v[46:47] neg_lo:[0,1] neg_hi:[0,1]
	v_pk_add_f32 v[12:13], v[12:13], v[88:89] neg_lo:[0,1] neg_hi:[0,1]
	v_pk_add_f32 v[44:45], v[44:45], v[90:91] neg_lo:[0,1] neg_hi:[0,1]
	v_add_f32_e32 v13, v96, v13
	v_add_f32_e32 v38, v97, v45
	v_add_f32_e32 v12, v12, v13
	v_add_f32_e32 v44, v44, v38
	v_add_f32_e32 v13, v39, v12
	v_add_f32_e32 v45, v47, v44
	v_mul_f32_e32 v89, v94, v13
	v_mul_f32_e32 v91, v95, v45
	v_mul_f32_e32 v38, v92, v89
	v_sub_f32_e32 v39, v39, v13
	v_add_f32_e32 v97, v98, v89
	v_mul_f32_e32 v46, v93, v91
	v_fma_f32 v88, v89, v92, -v38
	v_add_f32_e32 v96, v12, v39
	v_add_f32_e32 v101, v99, v91
	v_sub_f32_e32 v12, v97, v98
	v_fma_f32 v90, v91, v93, -v46
	v_fmac_f32_e32 v88, v89, v43
	v_sub_f32_e32 v47, v47, v45
	v_sub_f32_e32 v39, v101, v99
	v_sub_f32_e32 v43, v89, v12
	v_fmac_f32_e32 v90, v91, v31
	v_add_f32_e32 v12, v38, v88
	v_add_f32_e32 v100, v44, v47
	v_sub_f32_e32 v31, v91, v39
	v_add_f32_e32 v44, v46, v90
	v_sub_f32_e32 v39, v13, v12
	v_mov_b32_e32 v89, v12
	v_sub_f32_e32 v47, v45, v44
	v_pk_add_f32 v[12:13], v[12:13], v[38:39] neg_lo:[0,1] neg_hi:[0,1]
	v_mov_b32_e32 v91, v44
	v_pk_add_f32 v[44:45], v[44:45], v[46:47] neg_lo:[0,1] neg_hi:[0,1]
	v_pk_add_f32 v[12:13], v[12:13], v[88:89] neg_lo:[0,1] neg_hi:[0,1]
	v_pk_add_f32 v[44:45], v[44:45], v[90:91] neg_lo:[0,1] neg_hi:[0,1]
	v_add_f32_e32 v13, v96, v13
	v_add_f32_e32 v38, v100, v45
	v_add_f32_e32 v12, v12, v13
	v_add_f32_e32 v13, v44, v38
	v_add_f32_e32 v12, v39, v12
	v_add_f32_e32 v13, v47, v13
	v_mul_f32_e32 v12, v94, v12
	v_mul_f32_e32 v13, v95, v13
	v_add_f32_e32 v12, v43, v12
	v_cvt_f32_i32_e32 v30, v30
	v_add_f32_e32 v38, v31, v13
	v_add_f32_e32 v31, v97, v12
	v_mul_f32_e32 v44, v31, v31
	v_cvt_f32_i32_e32 v42, v42
	v_add_f32_e32 v43, v101, v38
	v_fmamk_f32 v88, v44, 0x3e9b6dac, v155
	v_sub_f32_e32 v45, v31, v97
	v_ldexp_f32 v13, v31, 1
	v_mul_f32_e32 v46, v43, v43
	v_mul_f32_e32 v31, v31, v44
	v_fmaak_f32 v131, v44, v88, 0x3f2aaada
	v_sub_f32_e32 v12, v12, v45
	v_fmamk_f32 v45, v46, 0x3e9b6dac, v155
	v_pk_mul_f32 v[40:41], v[30:31], v[130:131]
	v_sub_f32_e32 v47, v43, v101
	v_ldexp_f32 v39, v43, 1
	v_mul_f32_e32 v43, v43, v46
	v_ldexp_f32 v90, v12, 1
	v_fmaak_f32 v131, v46, v45, 0x3f2aaada
	v_fma_f32 v12, v30, s27, -v40
	v_sub_f32_e32 v38, v38, v47
	v_pk_mul_f32 v[46:47], v[42:43], v[130:131]
	v_fmac_f32_e32 v12, 0xb102e308, v30
	v_ldexp_f32 v94, v38, 1
	v_fma_f32 v38, v42, s27, -v46
	v_pk_add_f32 v[88:89], v[40:41], v[12:13]
	v_fmac_f32_e32 v38, 0xb102e308, v42
	v_sub_f32_e32 v11, v89, v13
	v_pk_add_f32 v[92:93], v[46:47], v[38:39]
	v_sub_f32_e32 v11, v41, v11
	v_mov_b32_e32 v44, v40
	v_sub_f32_e32 v31, v93, v39
	v_add_f32_e32 v45, v90, v11
	v_mov_b32_e32 v30, v46
	v_pk_add_f32 v[42:43], v[88:89], v[40:41] neg_lo:[0,1] neg_hi:[0,1]
	v_pk_add_f32 v[40:41], v[92:93], v[46:47] neg_lo:[0,1] neg_hi:[0,1]
	v_sub_f32_e32 v11, v47, v31
	v_pk_add_f32 v[46:47], v[88:89], v[44:45]
	v_mov_b32_e32 v13, v88
	v_add_f32_e32 v31, v94, v11
	v_mov_b32_e32 v43, v47
	v_pk_add_f32 v[96:97], v[92:93], v[30:31]
	v_mov_b32_e32 v94, v31
	v_pk_add_f32 v[30:31], v[12:13], v[42:43] neg_lo:[0,1] neg_hi:[0,1]
	v_pk_add_f32 v[12:13], v[12:13], v[42:43]
	v_mov_b32_e32 v39, v92
	v_mov_b32_e32 v41, v97
	v_pk_add_f32 v[98:99], v[12:13], v[88:89] op_sel:[1,0] op_sel_hi:[0,1] neg_lo:[0,1] neg_hi:[0,1]
	v_mov_b32_e32 v90, v45
	v_mov_b32_e32 v44, v47
	v_mov_b32_e32 v45, v13
	v_pk_add_f32 v[100:101], v[38:39], v[40:41] neg_lo:[0,1] neg_hi:[0,1]
	v_pk_add_f32 v[38:39], v[38:39], v[40:41]
	v_pk_add_f32 v[40:41], v[46:47], v[98:99] op_sel_hi:[1,0] neg_lo:[0,1] neg_hi:[0,1]
	v_pk_mov_b32 v[46:47], v[88:89], v[98:99] op_sel:[1,0]
	v_mov_b32_e32 v91, v88
	v_pk_add_f32 v[88:89], v[38:39], v[92:93] op_sel:[1,0] op_sel_hi:[0,1] neg_lo:[0,1] neg_hi:[0,1]
	v_pk_add_f32 v[44:45], v[44:45], v[46:47] neg_lo:[0,1] neg_hi:[0,1]
	v_mov_b32_e32 v42, v97
	v_mov_b32_e32 v43, v39
	v_mov_b32_e32 v40, v30
	v_pk_add_f32 v[46:47], v[96:97], v[88:89] op_sel_hi:[1,0] neg_lo:[0,1] neg_hi:[0,1]
	v_pk_mov_b32 v[88:89], v[92:93], v[88:89] op_sel:[1,0]
	v_pk_add_f32 v[44:45], v[90:91], v[44:45] neg_lo:[0,1] neg_hi:[0,1]
	v_mov_b32_e32 v95, v92
	v_pk_add_f32 v[42:43], v[42:43], v[88:89] neg_lo:[0,1] neg_hi:[0,1]
	v_pk_add_f32 v[40:41], v[40:41], v[44:45]
	v_mov_b32_e32 v46, v100
	v_pk_add_f32 v[42:43], v[94:95], v[42:43] neg_lo:[0,1] neg_hi:[0,1]
	v_pk_add_f32 v[88:89], v[40:41], v[40:41] op_sel:[0,1] op_sel_hi:[1,0]
	v_mov_b32_e32 v31, v13
	v_pk_add_f32 v[46:47], v[46:47], v[42:43]
	v_pk_add_f32 v[12:13], v[12:13], v[88:89] op_sel:[1,0] op_sel_hi:[0,1]
	v_mov_b32_e32 v45, v88
	v_pk_add_f32 v[88:89], v[46:47], v[46:47] op_sel:[0,1] op_sel_hi:[1,0]
	v_mov_b32_e32 v41, v12
	v_mov_b32_e32 v101, v39
	v_pk_add_f32 v[38:39], v[38:39], v[88:89] op_sel:[1,0] op_sel_hi:[0,1]
	v_mov_b32_e32 v43, v88
	v_pk_add_f32 v[88:89], v[40:41], v[30:31] neg_lo:[0,1] neg_hi:[0,1]
	v_mov_b32_e32 v47, v38
	v_sub_f32_e32 v11, v40, v88
	v_pk_add_f32 v[44:45], v[44:45], v[88:89] neg_lo:[0,1] neg_hi:[0,1]
	v_pk_add_f32 v[40:41], v[46:47], v[100:101] neg_lo:[0,1] neg_hi:[0,1]
	v_sub_f32_e32 v11, v30, v11
	v_sub_f32_e32 v13, v46, v40
	v_add_f32_e32 v11, v44, v11
	v_pk_add_f32 v[30:31], v[42:43], v[40:41] neg_lo:[0,1] neg_hi:[0,1]
	v_sub_f32_e32 v13, v100, v13
	v_add_f32_e32 v11, v11, v45
	v_add_f32_e32 v13, v30, v13
	v_add_f32_e32 v11, v12, v11
	v_cmp_nlt_f32_e32 vcc, 1.0, v81
	s_waitcnt vmcnt(0) lgkmcnt(0)
	ds_write_b128 v10, v[0:3]
	s_waitcnt lgkmcnt(0)
	s_barrier
; DI float fexp2(float x) { return __builtin_amdgcn_exp2f(x); }
; DI f32x4 mfma16(bf16x8 a, bf16x8 b, f32x4 c) { return __builtin_amdgcn_mfma_f32_16x16x32_bf16(a, b, c, 0, 0, 0); }
; DI void ret_out_phase(const Params& P, LAS unsigned char* lds, int r, const bf16* QKV, const bf16* ST, bf16* CAT) {
;     ...
; #pragma unroll
;             for (int ks = 0; ks < 4; ++ks) { const bf16x8 qb = frag_row(RA, PITCH, 16 * wave, 32 * ks, lane);
; #pragma unroll
;                 for (int t = 0; t < 8; ++t) sacc[t] = mfma16(frag_row(RB, PITCH, 16 * t, 32 * ks, lane), qb, sacc[t]); }
; #pragma unroll
;             for (int t = 0; t < 8; ++t)
; #pragma unroll
;                 for (int i = 0; i < 4; ++i) { const int dd = itok - (16 * t + 4 * g + i);
;                     sacc[t][i] *= dd >= 0 ? fexp2((float)dd * l2f) : fexp2((float)(-dd) * l2b); }
	ds_read_b128 v[0:3], v136 offset:34816
	v_add_f32_e32 v12, v13, v31
	v_cndmask_b32_e32 v11, v168, v11, vcc
	v_cmp_neq_f32_e32 vcc, 1.0, v81
	v_add_f32_e32 v12, v38, v12
	v_cmp_lt_f32_e64 s[0:1], |v81|, s28
	v_cndmask_b32_e32 v11, v169, v11, vcc
	v_cmp_nlt_f32_e32 vcc, 1.0, v29
	v_cndmask_b32_e64 v31, v11, -v81, s[0:1]
	v_cmp_lt_f32_e64 s[0:1], |v29|, s28
	v_cndmask_b32_e32 v30, v168, v12, vcc
	v_cmp_neq_f32_e32 vcc, 1.0, v29
	v_mul_f32_e32 v102, 0x3fb8aa3b, v31
	ds_read_b128 v[10:13], v135
	ds_read_b128 v[38:41], v136 offset:39168
	ds_read_b128 v[42:45], v136 offset:43520
	ds_read_b128 v[88:91], v135 offset:64
	ds_read_b128 v[92:95], v136 offset:34880
	v_cndmask_b32_e32 v30, v169, v30, vcc
	v_cndmask_b32_e64 v29, v30, -v29, s[0:1]
	v_mul_f32_e32 v81, 0x3fb8aa3b, v29
	v_cmp_gt_i32_e32 vcc, 0, v36
	s_waitcnt lgkmcnt(4)
	v_mfma_f32_16x16x32_bf16 v[0:3], v[0:3], v[10:13], 0
	ds_read_b128 v[96:99], v136 offset:47872
	ds_read_b128 v[138:141], v136 offset:39232
	v_cndmask_b32_e32 v46, v102, v81, vcc
	v_cmp_gt_i32_e32 vcc, 0, v14
	ds_read_b128 v[142:145], v136 offset:52224
	ds_read_b128 v[146:149], v136 offset:43584
	v_cndmask_b32_e32 v14, v102, v81, vcc
	v_cmp_gt_i32_e32 vcc, 0, v8
	ds_read_b128 v[172:175], v136 offset:56576
	ds_read_b128 v[176:179], v136 offset:47936
	ds_read_b128 v[180:183], v136 offset:60928
	ds_read_b128 v[184:187], v136 offset:52288
	ds_read_b128 v[188:191], v136 offset:65280
	ds_read_b128 v[192:195], v136 offset:56640
	v_cndmask_b32_e32 v47, v102, v81, vcc
	v_cmp_gt_i32_e32 vcc, 0, v9
	s_waitcnt lgkmcnt(13)
	v_mfma_f32_16x16x32_bf16 v[38:41], v[38:41], v[10:13], 0
	ds_read_b128 v[196:199], v136 offset:60992
	v_cndmask_b32_e32 v100, v102, v81, vcc
	v_cmp_gt_i32_e32 vcc, 0, v15
	s_waitcnt lgkmcnt(13)
	v_mfma_f32_16x16x32_bf16 v[42:45], v[42:45], v[10:13], 0
	ds_read_b128 v[200:203], v136 offset:65344
	v_cndmask_b32_e32 v101, v102, v81, vcc
	v_cmp_gt_i32_e32 vcc, 0, v20
	s_waitcnt lgkmcnt(11)
	v_mfma_f32_16x16x32_bf16 v[96:99], v[96:99], v[10:13], 0
	v_mul_f32_e32 v46, v46, v103
	v_cndmask_b32_e32 v131, v102, v81, vcc
	v_cmp_gt_i32_e32 vcc, 0, v21
	s_waitcnt lgkmcnt(9)
	v_mfma_f32_16x16x32_bf16 v[142:145], v[142:145], v[10:13], 0
	v_mul_f32_e32 v103, v14, v151
	v_mul_f32_e32 v47, v47, v214
	v_mul_f32_e32 v101, v101, v171
	s_waitcnt lgkmcnt(7)
	v_mfma_f32_16x16x32_bf16 v[172:175], v[172:175], v[10:13], 0
	v_mul_f32_e32 v131, v131, v204
	v_mul_f32_e32 v100, v100, v215
	v_exp_f32_e32 v46, v46
	s_waitcnt lgkmcnt(5)
	v_mfma_f32_16x16x32_bf16 v[180:183], v[180:183], v[10:13], 0
	s_movk_i32 s0, 0x2000
	s_waitcnt lgkmcnt(3)
	v_mfma_f32_16x16x32_bf16 v[10:13], v[188:191], v[10:13], 0
	v_cndmask_b32_e32 v188, v102, v81, vcc
	v_cmp_gt_i32_e32 vcc, 0, v22
	v_mul_f32_e32 v151, v188, v205
	v_mfma_f32_16x16x32_bf16 v[0:3], v[92:95], v[88:91], v[0:3]
	ds_read_b128 v[92:95], v136 offset:34944
	v_cndmask_b32_e32 v216, v102, v81, vcc
	v_cmp_gt_i32_e32 vcc, 0, v23
	v_mfma_f32_16x16x32_bf16 v[38:41], v[138:141], v[88:91], v[38:41]
	s_nop 0
	v_cndmask_b32_e32 v217, v102, v81, vcc
	v_cmp_gt_i32_e32 vcc, 0, v24
	v_mfma_f32_16x16x32_bf16 v[20:23], v[146:149], v[88:91], v[42:45]
	s_nop 0
	v_cndmask_b32_e32 v218, v102, v81, vcc
	v_cmp_gt_i32_e32 vcc, 0, v25
	v_mfma_f32_16x16x32_bf16 v[42:45], v[176:179], v[88:91], v[96:99]
	s_nop 0
	v_cndmask_b32_e32 v219, v102, v81, vcc
	v_cmp_gt_i32_e32 vcc, 0, v26
	s_waitcnt lgkmcnt(2)
	v_mfma_f32_16x16x32_bf16 v[96:99], v[196:199], v[88:91], v[180:183]
	v_cndmask_b32_e32 v220, v102, v81, vcc
	v_cmp_gt_i32_e32 vcc, 0, v27
	v_mfma_f32_16x16x32_bf16 v[24:27], v[184:187], v[88:91], v[142:145]
	ds_read_b128 v[138:141], v135 offset:128
	s_nop 1
	ds_read_b128 v[142:145], v136 offset:39296
	v_cndmask_b32_e32 v221, v102, v81, vcc
	v_cmp_gt_i32_e32 vcc, 0, v28
	v_mfma_f32_16x16x32_bf16 v[28:31], v[192:195], v[88:91], v[172:175]
	s_nop 0
	v_cndmask_b32_e32 v222, v102, v81, vcc
	v_cmp_gt_i32_e32 vcc, 0, v85
	s_waitcnt lgkmcnt(3)
	v_mfma_f32_16x16x32_bf16 v[8:11], v[200:203], v[88:91], v[10:13]
	s_nop 2
	ds_read_b128 v[12:15], v136 offset:43648
	ds_read_b128 v[88:91], v135 offset:192
	ds_read_b128 v[146:149], v136 offset:35008
	v_cndmask_b32_e32 v85, v102, v81, vcc
	v_cmp_gt_i32_e32 vcc, 0, v86
	s_waitcnt lgkmcnt(4)
	v_mfma_f32_16x16x32_bf16 v[0:3], v[92:95], v[138:141], v[0:3]
	ds_read_b128 v[92:95], v136 offset:48000
	ds_read_b128 v[172:175], v136 offset:39360
	v_cndmask_b32_e32 v86, v102, v81, vcc
	v_cmp_gt_i32_e32 vcc, 0, v87
	s_waitcnt lgkmcnt(5)
	v_mfma_f32_16x16x32_bf16 v[38:41], v[142:145], v[138:141], v[38:41]
	ds_read_b128 v[142:145], v136 offset:52352
	ds_read_b128 v[176:179], v136 offset:43712
	v_cndmask_b32_e32 v87, v102, v81, vcc
	s_waitcnt lgkmcnt(6)
	v_mfma_f32_16x16x32_bf16 v[12:15], v[12:15], v[138:141], v[20:23]
	s_nop 2
	ds_read_b128 v[20:23], v136 offset:56704
	ds_read_b128 v[180:183], v136 offset:48064
	s_waitcnt lgkmcnt(5)
	v_mfma_f32_16x16x32_bf16 v[42:45], v[92:95], v[138:141], v[42:45]
	ds_read_b128 v[92:95], v136 offset:61056
	ds_read_b128 v[184:187], v136 offset:52416
	s_waitcnt lgkmcnt(5)
	v_mfma_f32_16x16x32_bf16 v[24:27], v[142:145], v[138:141], v[24:27]
	ds_read_b128 v[142:145], v136 offset:65408
	ds_read_b128 v[188:191], v136 offset:56768
	ds_read_b128 v[192:195], v136 offset:61120
	s_waitcnt lgkmcnt(4)
	v_mfma_f32_16x16x32_bf16 v[92:95], v[92:95], v[138:141], v[96:99]
	s_nop 2
	ds_read_b128 v[96:99], v136 offset:65472
	v_mfma_f32_16x16x32_bf16 v[20:23], v[20:23], v[138:141], v[28:31]
	s_waitcnt lgkmcnt(3)
; DI unsigned pk2(float lo, float hi) { return pg8::cvt_pk_bf16(lo, hi); }
; DI float fexp2(float x) { return __builtin_amdgcn_exp2f(x); }
; DI void ret_out_phase(const Params& P, LAS unsigned char* lds, int r, const bf16* QKV, const bf16* ST, bf16* CAT) {
;     ...
;         v4u sbr[4];
;         _Pragma("unroll") for (int it_ = 0; it_ < 4; ++it_) { const int task = tid + 512 * it_; sbr[it_] = __builtin_nontemporal_load((const v4u*)(stb + (task >> 4) * 128 + (task & 15) * 8)); }
;         const size_t tok = (size_t)(tokbase + 16 * wave + li);
;         v2u gtv[8];
; #pragma unroll
;         for (int t = 0; t < 8; ++t) gtv[t] = *(const v2u*)(QKV + tok * NIN0 + 4608 + h * 128 + 16 * t + 4 * g);
;     ...
; #pragma unroll
;             for (int t = 0; t < 8; ++t)
; #pragma unroll
;                 for (int i = 0; i < 4; ++i) { const int dd = itok - (16 * t + 4 * g + i);
;                     sacc[t][i] *= dd >= 0 ? fexp2((float)dd * l2f) : fexp2((float)(-dd) * l2b); }
; #pragma unroll
;             for (int sx = 0; sx < 4; ++sx) { v4u w; w.x = pk2(sacc[2 * sx][0], sacc[2 * sx][1]); w.y = pk2(sacc[2 * sx][2], sacc[2 * sx][3]);
;                 w.z = pk2(sacc[2 * sx + 1][0], sacc[2 * sx + 1][1]); w.w = pk2(sacc[2 * sx + 1][2], sacc[2 * sx + 1][3]); pf[sx] = __builtin_bit_cast(bf16x8, w); }
	v_mfma_f32_16x16x32_bf16 v[138:141], v[142:145], v[138:141], v[8:11]
	s_nop 0
	v_mul_f32_e32 v28, v216, v37
	v_mul_f32_e32 v29, v217, v206
	v_mul_f32_e32 v30, v218, v207
	v_mfma_f32_16x16x32_bf16 v[142:145], v[146:149], v[88:91], v[0:3]
	v_mul_f32_e32 v8, v220, v209
	v_mul_f32_e32 v9, v221, v210
	v_mul_f32_e32 v10, v222, v211
	v_mul_f32_e32 v0, v85, v212
	v_mul_f32_e32 v1, v86, v213
	v_mfma_f32_16x16x32_bf16 v[146:149], v[172:175], v[88:91], v[38:41]
	v_exp_f32_e32 v85, v131
	v_exp_f32_e32 v86, v151
	v_exp_f32_e32 v131, v9
	v_exp_f32_e32 v40, v47
	v_exp_f32_e32 v47, v101
	v_mfma_f32_16x16x32_bf16 v[172:175], v[176:179], v[88:91], v[12:15]
	v_exp_f32_e32 v38, v103
	v_exp_f32_e32 v41, v100
	v_exp_f32_e32 v100, v30
	v_mfma_f32_16x16x32_bf16 v[176:179], v[180:183], v[88:91], v[42:45]
	v_exp_f32_e32 v103, v8
	v_exp_f32_e32 v151, v10
	v_exp_f32_e32 v171, v0
	v_mul_f32_e32 v44, v47, v146
	v_mul_f32_e32 v47, v85, v147
	v_mul_f32_e32 v85, v86, v148
	v_cvt_f32_u32_e32 v86, v150
	v_exp_f32_e32 v42, v28
	v_exp_f32_e32 v45, v29
	v_mfma_f32_16x16x32_bf16 v[28:31], v[184:187], v[88:91], v[24:27]
	v_exp_f32_e32 v180, v1
	flat_load_dwordx4 v[12:15], v[4:5] nt
	flat_load_dwordx4 v[8:11], v[6:7] nt
	s_nop 0
	flat_load_dwordx4 v[4:7], v[16:17] nt
	flat_load_dwordx4 v[0:3], v[18:19] nt
	v_mul_f32_e32 v86, v87, v86
	s_waitcnt lgkmcnt(0)
	v_mfma_f32_16x16x32_bf16 v[24:27], v[188:191], v[88:91], v[20:23]
	v_add_u32_e32 v87, 0xffffffbf, v36
	v_exp_f32_e32 v86, v86
	v_cmp_gt_i32_e32 vcc, 0, v87
	v_mfma_f32_16x16x32_bf16 v[20:23], v[192:195], v[88:91], v[92:95]
	v_mul_f32_e32 v37, v219, v208
	v_mul_f32_e32 v28, v86, v28
	v_cndmask_b32_e32 v86, v102, v81, vcc
	v_mfma_f32_16x16x32_bf16 v[16:19], v[96:99], v[88:91], v[138:141]
	v_sub_u32_e32 v88, 0x41, v36
	v_max_i32_e32 v88, v87, v88
	v_cvt_f32_u32_e32 v88, v88
	v_add_u32_e32 v87, 0xffffffbe, v36
	v_cmp_gt_i32_e32 vcc, 0, v87
	v_exp_f32_e32 v101, v37
	v_mul_f32_e32 v86, v86, v88
	v_sub_u32_e32 v88, 0x42, v36
	v_exp_f32_e32 v86, v86
	v_max_i32_e32 v88, v87, v88
	v_cvt_f32_u32_e32 v88, v88
	v_add_u32_e32 v87, 0xffffffbd, v36
	v_mul_f32_e32 v29, v86, v29
	v_cndmask_b32_e32 v86, v102, v81, vcc
	v_mul_f32_e32 v86, v86, v88
	v_sub_u32_e32 v88, 0x43, v36
	v_exp_f32_e32 v86, v86
	v_max_i32_e32 v88, v87, v88
	v_cvt_f32_u32_e32 v88, v88
	v_cmp_gt_i32_e32 vcc, 0, v87
	v_mul_f32_e32 v30, v86, v30
	v_add_u32_e32 v87, 0xffffffb0, v36
	v_cndmask_b32_e32 v86, v102, v81, vcc
	v_mul_f32_e32 v86, v86, v88
	v_sub_u32_e32 v88, 0x50, v36
	v_exp_f32_e32 v86, v86
	v_max_i32_e32 v88, v87, v88
	v_cvt_f32_u32_e32 v88, v88
	v_cmp_gt_i32_e32 vcc, 0, v87
	v_mul_f32_e32 v31, v86, v31
	v_add_u32_e32 v87, 0xffffffaf, v36
	v_cndmask_b32_e32 v86, v102, v81, vcc
	v_mul_f32_e32 v86, v86, v88
	v_sub_u32_e32 v88, 0x51, v36
	v_exp_f32_e32 v86, v86
	v_max_i32_e32 v88, v87, v88
	v_cvt_f32_u32_e32 v88, v88
	v_cmp_gt_i32_e32 vcc, 0, v87
	v_mul_f32_e32 v140, v86, v24
	v_add_u32_e32 v86, 0xffffffae, v36
	v_cndmask_b32_e32 v24, v102, v81, vcc
	v_mul_f32_e32 v24, v24, v88
	v_sub_u32_e32 v87, 0x52, v36
	v_exp_f32_e32 v24, v24
	v_max_i32_e32 v87, v86, v87
	v_cvt_f32_u32_e32 v87, v87
	v_cmp_gt_i32_e32 vcc, 0, v86
	v_mul_f32_e32 v141, v24, v25
	v_add_u32_e32 v25, 0xffffffad, v36
	v_cndmask_b32_e32 v24, v102, v81, vcc
	v_mul_f32_e32 v24, v24, v87
	v_sub_u32_e32 v86, 0x53, v36
	v_exp_f32_e32 v24, v24
	v_max_i32_e32 v86, v25, v86
	v_cvt_f32_u32_e32 v86, v86
	v_cmp_gt_i32_e32 vcc, 0, v25
	v_mul_f32_e32 v37, v46, v142
	v_mul_f32_e32 v142, v24, v26
	v_cndmask_b32_e32 v24, v102, v81, vcc
	v_mul_f32_e32 v24, v24, v86
	v_add_u32_e32 v25, 0xffffffa0, v36
	v_sub_u32_e32 v26, 0x60, v36
	v_exp_f32_e32 v24, v24
	v_max_i32_e32 v26, v25, v26
	v_cvt_f32_u32_e32 v26, v26
	v_cmp_gt_i32_e32 vcc, 0, v25
	v_mul_f32_e32 v27, v24, v27
	v_add_u32_e32 v25, 0xffffff9f, v36
	v_cndmask_b32_e32 v24, v102, v81, vcc
	v_mul_f32_e32 v24, v24, v26
	v_sub_u32_e32 v26, 0x61, v36
	v_exp_f32_e32 v24, v24
	v_max_i32_e32 v26, v25, v26
	v_cvt_f32_u32_e32 v26, v26
	v_cmp_gt_i32_e32 vcc, 0, v25
	v_mul_f32_e32 v39, v38, v143
	v_mul_f32_e32 v143, v24, v20
	v_cndmask_b32_e32 v20, v102, v81, vcc
	v_mul_f32_e32 v20, v20, v26
	v_add_u32_e32 v24, 0xffffff9e, v36
	v_sub_u32_e32 v25, 0x62, v36
	v_exp_f32_e32 v20, v20
	v_max_i32_e32 v25, v24, v25
	v_cvt_f32_u32_e32 v25, v25
	v_cmp_gt_i32_e32 vcc, 0, v24
	v_mul_f32_e32 v40, v40, v144
	v_mul_f32_e32 v144, v20, v21
	v_cndmask_b32_e32 v20, v102, v81, vcc
	v_mul_f32_e32 v20, v20, v25
	v_add_u32_e32 v21, 0xffffff9d, v36
	v_sub_u32_e32 v24, 0x63, v36
	v_exp_f32_e32 v20, v20
	v_max_i32_e32 v24, v21, v24
	v_cvt_f32_u32_e32 v24, v24
	v_cmp_gt_i32_e32 vcc, 0, v21
	v_mul_f32_e32 v43, v41, v145
	v_mul_f32_e32 v145, v20, v22
	v_cndmask_b32_e32 v20, v102, v81, vcc
	v_mul_f32_e32 v20, v20, v24
	v_exp_f32_e32 v22, v20
	v_add_co_u32_e32 v20, vcc, s0, v34
	v_mul_f32_e32 v138, v42, v149
	s_nop 0
	v_addc_co_u32_e32 v21, vcc, 0, v35, vcc
	v_mul_f32_e32 v41, v100, v173
	v_mul_f32_e32 v42, v101, v174
	flat_load_dwordx2 v[100:101], v[20:21] offset:1024
	flat_load_dwordx2 v[98:99], v[32:33] offset:32
	flat_load_dwordx2 v[96:97], v[32:33] offset:64
	flat_load_dwordx2 v[94:95], v[32:33] offset:96
	flat_load_dwordx2 v[92:93], v[32:33] offset:128
	flat_load_dwordx2 v[90:91], v[32:33] offset:160
	flat_load_dwordx2 v[88:89], v[32:33] offset:192
	flat_load_dwordx2 v[86:87], v[32:33] offset:224
	v_add_u32_e32 v20, 0xffffff90, v36
	v_sub_u32_e32 v21, 0x70, v36
	v_max_i32_e32 v21, v20, v21
	v_cvt_f32_u32_e32 v21, v21
	v_cmp_gt_i32_e32 vcc, 0, v20
	v_mul_f32_e32 v32, v22, v23
	v_sub_u32_e32 v22, 0x71, v36
	v_cndmask_b32_e32 v20, v102, v81, vcc
	v_mul_f32_e32 v20, v20, v21
	v_add_u32_e32 v21, 0xffffff8f, v36
; DI unsigned pk2(float lo, float hi) { return pg8::cvt_pk_bf16(lo, hi); }
; DI float fexp2(float x) { return __builtin_amdgcn_exp2f(x); }
; DI f32x4 mfma16(bf16x8 a, bf16x8 b, f32x4 c) { return __builtin_amdgcn_mfma_f32_16x16x32_bf16(a, b, c, 0, 0, 0); }
; DI void ret_out_phase(const Params& P, LAS unsigned char* lds, int r, const bf16* QKV, const bf16* ST, bf16* CAT) {
;     ...
; #pragma unroll
;             for (int t = 0; t < 8; ++t)
; #pragma unroll
;                 for (int i = 0; i < 4; ++i) { const int dd = itok - (16 * t + 4 * g + i);
;                     sacc[t][i] *= dd >= 0 ? fexp2((float)dd * l2f) : fexp2((float)(-dd) * l2b); }
; #pragma unroll
;             for (int sx = 0; sx < 4; ++sx) { v4u w; w.x = pk2(sacc[2 * sx][0], sacc[2 * sx][1]); w.y = pk2(sacc[2 * sx][2], sacc[2 * sx][3]);
;                 w.z = pk2(sacc[2 * sx + 1][0], sacc[2 * sx + 1][1]); w.w = pk2(sacc[2 * sx + 1][2], sacc[2 * sx + 1][3]); pf[sx] = __builtin_bit_cast(bf16x8, w); }
;         }
;         f32x4 yacc[8];
; #pragma unroll
;         for (int t = 0; t < 8; ++t) yacc[t] = (f32x4){0.f, 0.f, 0.f, 0.f};
; #pragma unroll
;         for (int sx = 0; sx < 4; ++sx)
; #pragma unroll
;             for (int t = 0; t < 8; ++t) { yacc[t] = mfma16(frag_tr2(RC, PITCH, 32 * sx, 32 * sx + 16, 16 * t, lane), pf[sx], yacc[t]); if ((t & 3) == 3) __builtin_amdgcn_sched_barrier(0); }
	v_max_i32_e32 v22, v21, v22
	v_cvt_f32_u32_e32 v22, v22
	v_cmp_gt_i32_e32 vcc, 0, v21
	v_sub_u32_e32 v23, 0x72, v36
	v_sub_u32_e32 v24, 0x73, v36
	v_cndmask_b32_e32 v21, v102, v81, vcc
	v_mul_f32_e32 v21, v21, v22
	v_add_u32_e32 v22, 0xffffff8e, v36
	v_max_i32_e32 v23, v22, v23
	v_cvt_f32_u32_e32 v23, v23
	v_cmp_gt_i32_e32 vcc, 0, v22
	v_exp_f32_e32 v20, v20
	v_exp_f32_e32 v21, v21
	v_cndmask_b32_e32 v22, v102, v81, vcc
	v_mul_f32_e32 v22, v22, v23
	v_add_u32_e32 v23, 0xffffff8d, v36
	v_max_i32_e32 v24, v23, v24
	v_cvt_f32_u32_e32 v24, v24
	v_cmp_gt_i32_e32 vcc, 0, v23
	v_exp_f32_e32 v22, v22
	v_mul_f32_e32 v38, v45, v172
	v_cndmask_b32_e32 v23, v102, v81, vcc
	v_mul_f32_e32 v23, v23, v24
	v_exp_f32_e32 v23, v23
	v_mul_f32_e32 v45, v103, v175
	v_mul_f32_e32 v46, v131, v176
	v_mul_f32_e32 v33, v20, v16
	v_mul_f32_e32 v34, v21, v17
	v_mul_f32_e32 v35, v22, v18
	v_mul_f32_e32 v36, v23, v19
	v_mul_f32_e32 v103, v151, v177
	v_mul_f32_e32 v131, v171, v178
	v_mul_f32_e32 v139, v180, v179
	v_cvt_pk_bf16_f32 v16, v37, v39
	v_cvt_pk_bf16_f32 v17, v40, v43
	v_cvt_pk_bf16_f32 v18, v44, v47
	v_cvt_pk_bf16_f32 v19, v85, v138
	v_cvt_pk_bf16_f32 v20, v38, v41
	v_cvt_pk_bf16_f32 v21, v42, v45
	v_cvt_pk_bf16_f32 v22, v46, v103
	v_cvt_pk_bf16_f32 v23, v131, v139
	v_cvt_pk_bf16_f32 v24, v28, v29
	v_cvt_pk_bf16_f32 v25, v30, v31
	v_cvt_pk_bf16_f32 v26, v140, v141
	v_cvt_pk_bf16_f32 v27, v142, v27
	v_cvt_pk_bf16_f32 v28, v143, v144
	v_cvt_pk_bf16_f32 v29, v145, v32
	v_cvt_pk_bf16_f32 v30, v33, v34
	v_cvt_pk_bf16_f32 v31, v35, v36
	ds_read_b64_tr_b16 v[32:33], v124
	ds_read_b64_tr_b16 v[34:35], v124 offset:4352
	ds_read_b64_tr_b16 v[38:39], v124 offset:4384
	ds_read_b64_tr_b16 v[36:37], v124 offset:32
	ds_read_b64_tr_b16 v[40:41], v124 offset:64
	ds_read_b64_tr_b16 v[44:45], v124 offset:96
	ds_read_b64_tr_b16 v[42:43], v124 offset:4416
	ds_read_b64_tr_b16 v[46:47], v124 offset:4448
	s_waitcnt lgkmcnt(0)
	v_mfma_f32_16x16x32_bf16 v[32:35], v[32:35], v[16:19], 0
	v_ashrrev_i32_e32 v85, 31, v84
	v_mfma_f32_16x16x32_bf16 v[36:39], v[36:39], v[16:19], 0
	v_mfma_f32_16x16x32_bf16 v[40:43], v[40:43], v[16:19], 0
	v_mfma_f32_16x16x32_bf16 v[44:47], v[44:47], v[16:19], 0
	ds_read_b64_tr_b16 v[138:139], v124 offset:128
	ds_read_b64_tr_b16 v[140:141], v124 offset:4480
	ds_read_b64_tr_b16 v[144:145], v124 offset:4512
	ds_read_b64_tr_b16 v[142:143], v124 offset:160
	ds_read_b64_tr_b16 v[146:147], v124 offset:192
	ds_read_b64_tr_b16 v[172:173], v124 offset:224
	ds_read_b64_tr_b16 v[148:149], v124 offset:4544
	ds_read_b64_tr_b16 v[174:175], v124 offset:4576
	s_waitcnt lgkmcnt(0)
	v_mfma_f32_16x16x32_bf16 v[138:141], v[138:141], v[16:19], 0
	v_mfma_f32_16x16x32_bf16 v[142:145], v[142:145], v[16:19], 0
	v_mfma_f32_16x16x32_bf16 v[146:149], v[146:149], v[16:19], 0
	v_mfma_f32_16x16x32_bf16 v[16:19], v[172:175], v[16:19], 0
	ds_read_b64_tr_b16 v[172:173], v124 offset:8704
	ds_read_b64_tr_b16 v[174:175], v124 offset:13056
	ds_read_b64_tr_b16 v[178:179], v124 offset:13088
	ds_read_b64_tr_b16 v[176:177], v124 offset:8736
	ds_read_b64_tr_b16 v[180:181], v124 offset:8768
	ds_read_b64_tr_b16 v[184:185], v124 offset:8800
	ds_read_b64_tr_b16 v[182:183], v124 offset:13120
	ds_read_b64_tr_b16 v[186:187], v124 offset:13152
	s_waitcnt lgkmcnt(0)
	v_mfma_f32_16x16x32_bf16 v[32:35], v[172:175], v[20:23], v[32:35]
	v_mfma_f32_16x16x32_bf16 v[36:39], v[176:179], v[20:23], v[36:39]
	v_mfma_f32_16x16x32_bf16 v[40:43], v[180:183], v[20:23], v[40:43]
	v_mfma_f32_16x16x32_bf16 v[44:47], v[184:187], v[20:23], v[44:47]
	ds_read_b64_tr_b16 v[172:173], v124 offset:8832
	ds_read_b64_tr_b16 v[174:175], v124 offset:13184
	ds_read_b64_tr_b16 v[178:179], v124 offset:13216
	ds_read_b64_tr_b16 v[176:177], v124 offset:8864
	ds_read_b64_tr_b16 v[180:181], v124 offset:8896
	ds_read_b64_tr_b16 v[184:185], v124 offset:8928
	ds_read_b64_tr_b16 v[182:183], v124 offset:13248
	ds_read_b64_tr_b16 v[186:187], v124 offset:13280
	s_waitcnt lgkmcnt(0)
	v_mfma_f32_16x16x32_bf16 v[138:141], v[172:175], v[20:23], v[138:141]
	v_mfma_f32_16x16x32_bf16 v[142:145], v[176:179], v[20:23], v[142:145]
	v_mfma_f32_16x16x32_bf16 v[146:149], v[180:183], v[20:23], v[146:149]
	v_mfma_f32_16x16x32_bf16 v[16:19], v[184:187], v[20:23], v[16:19]
	ds_read_b64_tr_b16 v[20:21], v124 offset:17408
	ds_read_b64_tr_b16 v[22:23], v124 offset:21760
	ds_read_b64_tr_b16 v[174:175], v124 offset:21792
	ds_read_b64_tr_b16 v[172:173], v124 offset:17440
	ds_read_b64_tr_b16 v[176:177], v124 offset:17472
	ds_read_b64_tr_b16 v[180:181], v124 offset:17504
	ds_read_b64_tr_b16 v[178:179], v124 offset:21824
	ds_read_b64_tr_b16 v[182:183], v124 offset:21856
	s_waitcnt lgkmcnt(0)
	v_mfma_f32_16x16x32_bf16 v[20:23], v[20:23], v[24:27], v[32:35]
	v_mfma_f32_16x16x32_bf16 v[32:35], v[172:175], v[24:27], v[36:39]
	v_mfma_f32_16x16x32_bf16 v[36:39], v[176:179], v[24:27], v[40:43]
	v_mfma_f32_16x16x32_bf16 v[172:175], v[180:183], v[24:27], v[44:47]
	s_nop 1
	ds_read_b64_tr_b16 v[40:41], v124 offset:17536
	ds_read_b64_tr_b16 v[42:43], v124 offset:21888
	ds_read_b64_tr_b16 v[46:47], v124 offset:21920
	ds_read_b64_tr_b16 v[44:45], v124 offset:17568
	ds_read_b64_tr_b16 v[176:177], v124 offset:17600
	ds_read_b64_tr_b16 v[180:181], v124 offset:17632
	ds_read_b64_tr_b16 v[178:179], v124 offset:21952
	ds_read_b64_tr_b16 v[182:183], v124 offset:21984
	s_waitcnt lgkmcnt(0)
; DI f32x4 mfma16(bf16x8 a, bf16x8 b, f32x4 c) { return __builtin_amdgcn_mfma_f32_16x16x32_bf16(a, b, c, 0, 0, 0); }
; DI void ret_out_phase(const Params& P, LAS unsigned char* lds, int r, const bf16* QKV, const bf16* ST, bf16* CAT) {
;     ...
;         for (int sx = 0; sx < 4; ++sx)
; #pragma unroll
;             for (int t = 0; t < 8; ++t) { yacc[t] = mfma16(frag_tr2(RC, PITCH, 32 * sx, 32 * sx + 16, 16 * t, lane), pf[sx], yacc[t]); if ((t & 3) == 3) __builtin_amdgcn_sched_barrier(0); }
;         {
;             f32x4 tacc[8];
; #pragma unroll
;             for (int t = 0; t < 8; ++t) tacc[t] = (f32x4){0.f, 0.f, 0.f, 0.f};
; #pragma unroll
;             for (int ks = 0; ks < 4; ++ks) { const bf16x8 qb = frag_row(RA, PITCH, 16 * wave, 32 * ks, lane);
; #pragma unroll
;                 for (int t = 0; t < 8; ++t) { tacc[t] = mfma16(frag_tr(RD, PITCH, 32 * ks, 16 * t, lane), qb, tacc[t]); if ((t & 3) == 3) __builtin_amdgcn_sched_barrier(0); } }
	v_mfma_f32_16x16x32_bf16 v[138:141], v[40:43], v[24:27], v[138:141]
	v_mfma_f32_16x16x32_bf16 v[142:145], v[44:47], v[24:27], v[142:145]
	v_mfma_f32_16x16x32_bf16 v[146:149], v[176:179], v[24:27], v[146:149]
	v_mfma_f32_16x16x32_bf16 v[176:179], v[180:183], v[24:27], v[16:19]
	s_nop 2
	ds_read_b64_tr_b16 v[16:17], v124 offset:26112
	ds_read_b64_tr_b16 v[18:19], v124 offset:30464
	ds_read_b64_tr_b16 v[26:27], v124 offset:30496
	ds_read_b64_tr_b16 v[24:25], v124 offset:26144
	ds_read_b64_tr_b16 v[180:181], v124 offset:26176
	ds_read_b64_tr_b16 v[184:185], v124 offset:26208
	ds_read_b64_tr_b16 v[182:183], v124 offset:30528
	ds_read_b64_tr_b16 v[186:187], v124 offset:30560
	s_waitcnt lgkmcnt(0)
	v_mfma_f32_16x16x32_bf16 v[44:47], v[16:19], v[28:31], v[20:23]
	v_mfma_f32_16x16x32_bf16 v[40:43], v[24:27], v[28:31], v[32:35]
	v_mfma_f32_16x16x32_bf16 v[36:39], v[180:183], v[28:31], v[36:39]
	v_mfma_f32_16x16x32_bf16 v[16:19], v[184:187], v[28:31], v[172:175]
	ds_read_b64_tr_b16 v[20:21], v124 offset:26240
	ds_read_b64_tr_b16 v[22:23], v124 offset:30592
	ds_read_b64_tr_b16 v[26:27], v124 offset:30624
	ds_read_b64_tr_b16 v[24:25], v124 offset:26272
	ds_read_b64_tr_b16 v[172:173], v124 offset:26304
	ds_read_b64_tr_b16 v[180:181], v124 offset:26336
	ds_read_b64_tr_b16 v[174:175], v124 offset:30656
	ds_read_b64_tr_b16 v[182:183], v124 offset:30688
	s_waitcnt lgkmcnt(0)
	v_mfma_f32_16x16x32_bf16 v[32:35], v[20:23], v[28:31], v[138:141]
	v_mfma_f32_16x16x32_bf16 v[24:27], v[24:27], v[28:31], v[142:145]
	v_mfma_f32_16x16x32_bf16 v[20:23], v[172:175], v[28:31], v[146:149]
	v_mfma_f32_16x16x32_bf16 v[28:31], v[180:183], v[28:31], v[176:179]
	ds_read_b64_tr_b16 v[140:141], v125 offset:1088
	ds_read_b64_tr_b16 v[138:139], v125
	ds_read_b128 v[142:145], v135
	ds_read_b64_tr_b16 v[148:149], v125 offset:1120
	ds_read_b64_tr_b16 v[146:147], v125 offset:32
	ds_read_b64_tr_b16 v[172:173], v125 offset:64
	ds_read_b64_tr_b16 v[176:177], v125 offset:96
	ds_read_b64_tr_b16 v[174:175], v125 offset:1152
	ds_read_b64_tr_b16 v[178:179], v125 offset:1184
	s_waitcnt lgkmcnt(0)
	v_mfma_f32_16x16x32_bf16 v[138:141], v[138:141], v[142:145], 0
	v_mfma_f32_16x16x32_bf16 v[146:149], v[146:149], v[142:145], 0
	v_mfma_f32_16x16x32_bf16 v[172:175], v[172:175], v[142:145], 0
	v_mfma_f32_16x16x32_bf16 v[176:179], v[176:179], v[142:145], 0
	ds_read_b64_tr_b16 v[180:181], v125 offset:128
	ds_read_b64_tr_b16 v[182:183], v125 offset:1216
	ds_read_b64_tr_b16 v[186:187], v125 offset:1248
	ds_read_b64_tr_b16 v[184:185], v125 offset:160
	ds_read_b64_tr_b16 v[188:189], v125 offset:192
	ds_read_b64_tr_b16 v[192:193], v125 offset:224
	ds_read_b64_tr_b16 v[190:191], v125 offset:1280
	ds_read_b64_tr_b16 v[194:195], v125 offset:1312
	s_waitcnt lgkmcnt(0)
	v_mfma_f32_16x16x32_bf16 v[180:183], v[180:183], v[142:145], 0
	v_mfma_f32_16x16x32_bf16 v[184:187], v[184:187], v[142:145], 0
	v_mfma_f32_16x16x32_bf16 v[188:191], v[188:191], v[142:145], 0
	v_mfma_f32_16x16x32_bf16 v[142:145], v[192:195], v[142:145], 0
	ds_read_b64_tr_b16 v[194:195], v125 offset:9792
	ds_read_b64_tr_b16 v[192:193], v125 offset:8704
	ds_read_b128 v[196:199], v135 offset:64
	ds_read_b64_tr_b16 v[202:203], v125 offset:9824
	ds_read_b64_tr_b16 v[200:201], v125 offset:8736
	ds_read_b64_tr_b16 v[204:205], v125 offset:8768
	ds_read_b64_tr_b16 v[208:209], v125 offset:8800
	ds_read_b64_tr_b16 v[206:207], v125 offset:9856
	ds_read_b64_tr_b16 v[210:211], v125 offset:9888
	s_waitcnt lgkmcnt(0)
	v_mfma_f32_16x16x32_bf16 v[138:141], v[192:195], v[196:199], v[138:141]
	v_mfma_f32_16x16x32_bf16 v[146:149], v[200:203], v[196:199], v[146:149]
	v_mfma_f32_16x16x32_bf16 v[172:175], v[204:207], v[196:199], v[172:175]
	v_mfma_f32_16x16x32_bf16 v[176:179], v[208:211], v[196:199], v[176:179]
	ds_read_b64_tr_b16 v[192:193], v125 offset:8832
	ds_read_b64_tr_b16 v[194:195], v125 offset:9920
	ds_read_b64_tr_b16 v[202:203], v125 offset:9952
	ds_read_b64_tr_b16 v[200:201], v125 offset:8864
	ds_read_b64_tr_b16 v[204:205], v125 offset:8896
	ds_read_b64_tr_b16 v[208:209], v125 offset:8928
	ds_read_b64_tr_b16 v[206:207], v125 offset:9984
	ds_read_b64_tr_b16 v[210:211], v125 offset:10016
	s_waitcnt lgkmcnt(0)
	v_mfma_f32_16x16x32_bf16 v[180:183], v[192:195], v[196:199], v[180:183]
	v_mfma_f32_16x16x32_bf16 v[184:187], v[200:203], v[196:199], v[184:187]
	v_mfma_f32_16x16x32_bf16 v[188:191], v[204:207], v[196:199], v[188:191]
	v_mfma_f32_16x16x32_bf16 v[142:145], v[208:211], v[196:199], v[142:145]
	ds_read_b64_tr_b16 v[194:195], v125 offset:18496
	ds_read_b64_tr_b16 v[192:193], v125 offset:17408
	ds_read_b128 v[196:199], v135 offset:128
	ds_read_b64_tr_b16 v[202:203], v125 offset:18528
	ds_read_b64_tr_b16 v[200:201], v125 offset:17440
	ds_read_b64_tr_b16 v[204:205], v125 offset:17472
	ds_read_b64_tr_b16 v[208:209], v125 offset:17504
	ds_read_b64_tr_b16 v[206:207], v125 offset:18560
	ds_read_b64_tr_b16 v[210:211], v125 offset:18592
	s_waitcnt lgkmcnt(0)
	v_mfma_f32_16x16x32_bf16 v[138:141], v[192:195], v[196:199], v[138:141]
	v_mfma_f32_16x16x32_bf16 v[146:149], v[200:203], v[196:199], v[146:149]
	v_mfma_f32_16x16x32_bf16 v[172:175], v[204:207], v[196:199], v[172:175]
	v_mfma_f32_16x16x32_bf16 v[176:179], v[208:211], v[196:199], v[176:179]
	ds_read_b64_tr_b16 v[192:193], v125 offset:17536
	ds_read_b64_tr_b16 v[194:195], v125 offset:18624
	ds_read_b64_tr_b16 v[202:203], v125 offset:18656
	ds_read_b64_tr_b16 v[200:201], v125 offset:17568
	ds_read_b64_tr_b16 v[204:205], v125 offset:17600
	ds_read_b64_tr_b16 v[208:209], v125 offset:17632
	ds_read_b64_tr_b16 v[206:207], v125 offset:18688
	ds_read_b64_tr_b16 v[210:211], v125 offset:18720
	s_waitcnt lgkmcnt(0)
; #define LAS __attribute__((address_space(3)))
; DI float fexp2(float x) { return __builtin_amdgcn_exp2f(x); }
; DI f32x4 mfma16(bf16x8 a, bf16x8 b, f32x4 c) { return __builtin_amdgcn_mfma_f32_16x16x32_bf16(a, b, c, 0, 0, 0); }
; DI void ret_out_phase(const Params& P, LAS unsigned char* lds, int r, const bf16* QKV, const bf16* ST, bf16* CAT) {
;     ...
;             for (int ks = 0; ks < 4; ++ks) { const bf16x8 qb = frag_row(RA, PITCH, 16 * wave, 32 * ks, lane);
; #pragma unroll
;                 for (int t = 0; t < 8; ++t) { tacc[t] = mfma16(frag_tr(RD, PITCH, 32 * ks, 16 * t, lane), qb, tacc[t]); if ((t & 3) == 3) __builtin_amdgcn_sched_barrier(0); } }
;             const float qd = fexp2((float)(itok + 1) * l2f);
; #pragma unroll
;             for (int t = 0; t < 8; ++t) yacc[t] = yacc[t] + tacc[t] * qd;
;         }
;         __syncthreads();
;         _Pragma("unroll") for (int it_ = 0; it_ < 4; ++it_) { const int task = tid + 512 * it_; *(LAS v4u*)(RB + (task >> 4) * PITCH + (task & 15) * 16) = sbr[it_]; }
;         __syncthreads();
;         {
;             f32x4 tacc[8];
; #pragma unroll
;             for (int t = 0; t < 8; ++t) tacc[t] = (f32x4){0.f, 0.f, 0.f, 0.f};
; #pragma unroll
;             for (int ks = 0; ks < 4; ++ks) { const bf16x8 qb = frag_row(RA, PITCH, 16 * wave, 32 * ks, lane);
; #pragma unroll
;                 for (int t = 0; t < 8; ++t) { tacc[t] = mfma16(frag_tr(RB, PITCH, 32 * ks, 16 * t, lane), qb, tacc[t]); if ((t & 3) == 3) __builtin_amdgcn_sched_barrier(0); } }
	v_mfma_f32_16x16x32_bf16 v[180:183], v[192:195], v[196:199], v[180:183]
	v_mfma_f32_16x16x32_bf16 v[184:187], v[200:203], v[196:199], v[184:187]
	v_mfma_f32_16x16x32_bf16 v[188:191], v[204:207], v[196:199], v[188:191]
	v_mfma_f32_16x16x32_bf16 v[142:145], v[208:211], v[196:199], v[142:145]
	ds_read_b64_tr_b16 v[194:195], v125 offset:27200
	ds_read_b64_tr_b16 v[192:193], v125 offset:26112
	ds_read_b128 v[196:199], v135 offset:192
	ds_read_b64_tr_b16 v[202:203], v125 offset:27232
	ds_read_b64_tr_b16 v[200:201], v125 offset:26144
	ds_read_b64_tr_b16 v[204:205], v125 offset:26176
	ds_read_b64_tr_b16 v[208:209], v125 offset:26208
	ds_read_b64_tr_b16 v[206:207], v125 offset:27264
	ds_read_b64_tr_b16 v[210:211], v125 offset:27296
	s_waitcnt lgkmcnt(0)
	v_mfma_f32_16x16x32_bf16 v[138:141], v[192:195], v[196:199], v[138:141]
	v_mfma_f32_16x16x32_bf16 v[146:149], v[200:203], v[196:199], v[146:149]
	v_mfma_f32_16x16x32_bf16 v[172:175], v[204:207], v[196:199], v[172:175]
	v_mfma_f32_16x16x32_bf16 v[176:179], v[208:211], v[196:199], v[176:179]
	ds_read_b64_tr_b16 v[192:193], v125 offset:26240
	ds_read_b64_tr_b16 v[194:195], v125 offset:27328
	ds_read_b64_tr_b16 v[202:203], v125 offset:27360
	ds_read_b64_tr_b16 v[200:201], v125 offset:26272
	ds_read_b64_tr_b16 v[204:205], v125 offset:26304
	ds_read_b64_tr_b16 v[208:209], v125 offset:26336
	ds_read_b64_tr_b16 v[206:207], v125 offset:27392
	ds_read_b64_tr_b16 v[210:211], v125 offset:27424
	s_waitcnt lgkmcnt(0)
	v_mfma_f32_16x16x32_bf16 v[180:183], v[192:195], v[196:199], v[180:183]
	v_mfma_f32_16x16x32_bf16 v[184:187], v[200:203], v[196:199], v[184:187]
	v_mfma_f32_16x16x32_bf16 v[188:191], v[204:207], v[196:199], v[188:191]
	v_mfma_f32_16x16x32_bf16 v[142:145], v[208:211], v[196:199], v[142:145]
	v_add_u32_e32 v103, 1, v137
	v_cvt_f32_i32_e32 v103, v103
	s_barrier
	v_mul_f32_e32 v102, v102, v103
	v_exp_f32_e32 v150, v102
	v_add_u32_e32 v102, v108, v117
	s_waitcnt vmcnt(0)
	ds_write_b128 v102, v[12:15] offset:34816
	v_add_u32_e32 v12, v108, v119
	ds_write_b128 v12, v[8:11] offset:34816
	v_add_u32_e32 v8, v108, v121
	ds_write_b128 v8, v[4:7] offset:34816
	v_add_u32_e32 v4, v108, v123
	v_pk_fma_f32 v[46:47], v[150:151], v[140:141], v[46:47] op_sel_hi:[0,1,1]
	v_pk_fma_f32 v[44:45], v[150:151], v[138:139], v[44:45] op_sel_hi:[0,1,1]
	v_pk_fma_f32 v[42:43], v[150:151], v[148:149], v[42:43] op_sel_hi:[0,1,1]
	v_pk_fma_f32 v[40:41], v[150:151], v[146:147], v[40:41] op_sel_hi:[0,1,1]
	v_pk_fma_f32 v[38:39], v[150:151], v[174:175], v[38:39] op_sel_hi:[0,1,1]
	v_pk_fma_f32 v[36:37], v[150:151], v[172:173], v[36:37] op_sel_hi:[0,1,1]
	ds_write_b128 v4, v[0:3] offset:34816
	s_waitcnt lgkmcnt(0)
	s_barrier
	ds_read_b64_tr_b16 v[4:5], v126 offset:35904
	ds_read_b64_tr_b16 v[2:3], v126 offset:34816
	ds_read_b128 v[138:141], v135
	ds_read_b64_tr_b16 v[8:9], v126 offset:35936
	ds_read_b64_tr_b16 v[6:7], v126 offset:34848
	ds_read_b64_tr_b16 v[146:147], v126 offset:34880
	ds_read_b64_tr_b16 v[172:173], v126 offset:34912
	ds_read_b64_tr_b16 v[148:149], v126 offset:35968
	ds_read_b64_tr_b16 v[174:175], v126 offset:36000
	v_pk_fma_f32 v[0:1], v[150:151], v[178:179], v[18:19] op_sel_hi:[0,1,1]
	s_waitcnt lgkmcnt(6)
	v_mfma_f32_16x16x32_bf16 v[192:195], v[2:5], v[138:141], 0
	v_fma_f32 v102, v150, v176, v16
	v_fma_f32 v103, v150, v177, v17
	v_pk_fma_f32 v[14:15], v[150:151], v[182:183], v[34:35] op_sel_hi:[0,1,1]
	v_pk_fma_f32 v[16:17], v[150:151], v[180:181], v[32:33] op_sel_hi:[0,1,1]
	s_waitcnt lgkmcnt(4)
	v_mfma_f32_16x16x32_bf16 v[32:35], v[6:9], v[138:141], 0
	v_fma_f32 v8, v150, v186, v26
	v_fma_f32 v9, v150, v187, v27
	v_pk_fma_f32 v[10:11], v[150:151], v[184:185], v[24:25] op_sel_hi:[0,1,1]
	v_pk_fma_f32 v[4:5], v[150:151], v[190:191], v[22:23] op_sel_hi:[0,1,1]
	s_waitcnt lgkmcnt(1)
	v_mfma_f32_16x16x32_bf16 v[22:25], v[146:149], v[138:141], 0
	v_fma_f32 v6, v150, v188, v20
	v_fma_f32 v7, v150, v189, v21
	v_pk_fma_f32 v[2:3], v[150:151], v[144:145], v[30:31] op_sel_hi:[0,1,1]
	v_pk_fma_f32 v[12:13], v[150:151], v[142:143], v[28:29] op_sel_hi:[0,1,1]
	s_waitcnt lgkmcnt(0)
	v_mfma_f32_16x16x32_bf16 v[18:21], v[172:175], v[138:141], 0
	ds_read_b64_tr_b16 v[26:27], v126 offset:34944
	ds_read_b64_tr_b16 v[28:29], v126 offset:36032
	ds_read_b64_tr_b16 v[144:145], v126 offset:36064
	ds_read_b64_tr_b16 v[142:143], v126 offset:34976
	ds_read_b64_tr_b16 v[146:147], v126 offset:35008
	ds_read_b64_tr_b16 v[172:173], v126 offset:35040
	ds_read_b64_tr_b16 v[148:149], v126 offset:36096
	ds_read_b64_tr_b16 v[174:175], v126 offset:36128
	s_waitcnt lgkmcnt(6)
	v_mfma_f32_16x16x32_bf16 v[26:29], v[26:29], v[138:141], 0
	s_waitcnt lgkmcnt(4)
	v_mfma_f32_16x16x32_bf16 v[142:145], v[142:145], v[138:141], 0
	s_waitcnt lgkmcnt(1)
	v_mfma_f32_16x16x32_bf16 v[146:149], v[146:149], v[138:141], 0
	s_waitcnt lgkmcnt(0)
	v_mfma_f32_16x16x32_bf16 v[138:141], v[172:175], v[138:141], 0
	ds_read_b64_tr_b16 v[174:175], v126 offset:44608
	ds_read_b64_tr_b16 v[172:173], v126 offset:43520
	ds_read_b128 v[176:179], v135 offset:64
	ds_read_b64_tr_b16 v[182:183], v126 offset:44640
	ds_read_b64_tr_b16 v[180:181], v126 offset:43552
	ds_read_b64_tr_b16 v[184:185], v126 offset:43584
	ds_read_b64_tr_b16 v[188:189], v126 offset:43616
	ds_read_b64_tr_b16 v[186:187], v126 offset:44672
	ds_read_b64_tr_b16 v[190:191], v126 offset:44704
	s_waitcnt lgkmcnt(6)
	v_mfma_f32_16x16x32_bf16 v[172:175], v[172:175], v[176:179], v[192:195]
	s_waitcnt lgkmcnt(4)
	v_mfma_f32_16x16x32_bf16 v[30:33], v[180:183], v[176:179], v[32:35]
	s_waitcnt lgkmcnt(1)
	v_mfma_f32_16x16x32_bf16 v[22:25], v[184:187], v[176:179], v[22:25]
	s_waitcnt lgkmcnt(0)
; DI float fexp2(float x) { return __builtin_amdgcn_exp2f(x); }
; DI f32x4 mfma16(bf16x8 a, bf16x8 b, f32x4 c) { return __builtin_amdgcn_mfma_f32_16x16x32_bf16(a, b, c, 0, 0, 0); }
; DI void ret_out_phase(const Params& P, LAS unsigned char* lds, int r, const bf16* QKV, const bf16* ST, bf16* CAT) {
;     ...
;             for (int ks = 0; ks < 4; ++ks) { const bf16x8 qb = frag_row(RA, PITCH, 16 * wave, 32 * ks, lane);
; #pragma unroll
;                 for (int t = 0; t < 8; ++t) { tacc[t] = mfma16(frag_tr(RB, PITCH, 32 * ks, 16 * t, lane), qb, tacc[t]); if ((t & 3) == 3) __builtin_amdgcn_sched_barrier(0); } }
;             const float qd = fexp2((float)(128 - itok) * l2b);
; #pragma unroll
;             for (int t = 0; t < 8; ++t) yacc[t] = yacc[t] + tacc[t] * qd;
;         }
;         float ss = 0.f;
; #pragma unroll
;         for (int t = 0; t < 8; ++t) ss += (yacc[t][0] * yacc[t][0] + yacc[t][1] * yacc[t][1]) + (yacc[t][2] * yacc[t][2] + yacc[t][3] * yacc[t][3]);
	v_mfma_f32_16x16x32_bf16 v[18:21], v[188:191], v[176:179], v[18:21]
	ds_read_b64_tr_b16 v[180:181], v126 offset:43648
	ds_read_b64_tr_b16 v[182:183], v126 offset:44736
	ds_read_b64_tr_b16 v[186:187], v126 offset:44768
	ds_read_b64_tr_b16 v[184:185], v126 offset:43680
	ds_read_b64_tr_b16 v[188:189], v126 offset:43712
	ds_read_b64_tr_b16 v[192:193], v126 offset:43744
	ds_read_b64_tr_b16 v[190:191], v126 offset:44800
	ds_read_b64_tr_b16 v[194:195], v126 offset:44832
	s_waitcnt lgkmcnt(6)
	v_mfma_f32_16x16x32_bf16 v[26:29], v[180:183], v[176:179], v[26:29]
	s_waitcnt lgkmcnt(4)
	v_mfma_f32_16x16x32_bf16 v[142:145], v[184:187], v[176:179], v[142:145]
	s_waitcnt lgkmcnt(1)
	v_mfma_f32_16x16x32_bf16 v[146:149], v[188:191], v[176:179], v[146:149]
	s_waitcnt lgkmcnt(0)
	v_mfma_f32_16x16x32_bf16 v[138:141], v[192:195], v[176:179], v[138:141]
	ds_read_b64_tr_b16 v[178:179], v126 offset:53312
	ds_read_b64_tr_b16 v[176:177], v126 offset:52224
	ds_read_b128 v[180:183], v135 offset:128
	ds_read_b64_tr_b16 v[186:187], v126 offset:53344
	ds_read_b64_tr_b16 v[184:185], v126 offset:52256
	ds_read_b64_tr_b16 v[188:189], v126 offset:52288
	ds_read_b64_tr_b16 v[192:193], v126 offset:52320
	ds_read_b64_tr_b16 v[190:191], v126 offset:53376
	ds_read_b64_tr_b16 v[194:195], v126 offset:53408
	s_waitcnt lgkmcnt(6)
	v_mfma_f32_16x16x32_bf16 v[172:175], v[176:179], v[180:183], v[172:175]
	s_waitcnt lgkmcnt(4)
	v_mfma_f32_16x16x32_bf16 v[30:33], v[184:187], v[180:183], v[30:33]
	s_waitcnt lgkmcnt(1)
	v_mfma_f32_16x16x32_bf16 v[22:25], v[188:191], v[180:183], v[22:25]
	s_waitcnt lgkmcnt(0)
	v_mfma_f32_16x16x32_bf16 v[18:21], v[192:195], v[180:183], v[18:21]
	ds_read_b64_tr_b16 v[176:177], v126 offset:52352
	ds_read_b64_tr_b16 v[178:179], v126 offset:53440
	ds_read_b64_tr_b16 v[186:187], v126 offset:53472
	ds_read_b64_tr_b16 v[184:185], v126 offset:52384
	ds_read_b64_tr_b16 v[188:189], v126 offset:52416
	ds_read_b64_tr_b16 v[192:193], v126 offset:52448
	ds_read_b64_tr_b16 v[190:191], v126 offset:53504
	ds_read_b64_tr_b16 v[194:195], v126 offset:53536
	s_waitcnt lgkmcnt(6)
	v_mfma_f32_16x16x32_bf16 v[26:29], v[176:179], v[180:183], v[26:29]
	s_waitcnt lgkmcnt(4)
	v_mfma_f32_16x16x32_bf16 v[142:145], v[184:187], v[180:183], v[142:145]
	s_waitcnt lgkmcnt(1)
	v_mfma_f32_16x16x32_bf16 v[146:149], v[188:191], v[180:183], v[146:149]
	s_waitcnt lgkmcnt(0)
	v_mfma_f32_16x16x32_bf16 v[138:141], v[192:195], v[180:183], v[138:141]
	ds_read_b64_tr_b16 v[178:179], v126 offset:62016
	ds_read_b64_tr_b16 v[176:177], v126 offset:60928
	ds_read_b128 v[180:183], v135 offset:192
	ds_read_b64_tr_b16 v[186:187], v126 offset:62048
	ds_read_b64_tr_b16 v[184:185], v126 offset:60960
	ds_read_b64_tr_b16 v[188:189], v126 offset:60992
	ds_read_b64_tr_b16 v[192:193], v126 offset:61024
	ds_read_b64_tr_b16 v[190:191], v126 offset:62080
	ds_read_b64_tr_b16 v[194:195], v126 offset:62112
	s_waitcnt lgkmcnt(6)
	v_mfma_f32_16x16x32_bf16 v[172:175], v[176:179], v[180:183], v[172:175]
	s_waitcnt lgkmcnt(4)
	v_mfma_f32_16x16x32_bf16 v[30:33], v[184:187], v[180:183], v[30:33]
	s_waitcnt lgkmcnt(1)
	v_mfma_f32_16x16x32_bf16 v[176:179], v[188:191], v[180:183], v[22:25]
	s_waitcnt lgkmcnt(0)
	v_mfma_f32_16x16x32_bf16 v[184:187], v[192:195], v[180:183], v[18:21]
	s_nop 2
	ds_read_b64_tr_b16 v[18:19], v126 offset:61056
	ds_read_b64_tr_b16 v[20:21], v126 offset:62144
	ds_read_b64_tr_b16 v[24:25], v126 offset:62176
	ds_read_b64_tr_b16 v[22:23], v126 offset:61088
	ds_read_b64_tr_b16 v[188:189], v126 offset:61120
	ds_read_b64_tr_b16 v[192:193], v126 offset:61152
	ds_read_b64_tr_b16 v[190:191], v126 offset:62208
	ds_read_b64_tr_b16 v[194:195], v126 offset:62240
	s_waitcnt lgkmcnt(6)
	v_mfma_f32_16x16x32_bf16 v[26:29], v[18:21], v[180:183], v[26:29]
	s_waitcnt lgkmcnt(4)
	v_mfma_f32_16x16x32_bf16 v[142:145], v[22:25], v[180:183], v[142:145]
	s_waitcnt lgkmcnt(1)
	v_mfma_f32_16x16x32_bf16 v[146:149], v[188:191], v[180:183], v[146:149]
	s_waitcnt lgkmcnt(0)
	v_mfma_f32_16x16x32_bf16 v[138:141], v[192:195], v[180:183], v[138:141]
	v_sub_u32_e32 v18, 0x80, v137
	v_cvt_f32_i32_e32 v18, v18
	v_cmp_lt_i32_e32 vcc, v163, v158
	v_mul_f32_e32 v18, v81, v18
	v_exp_f32_e32 v34, v18
	s_nop 0
	v_pk_fma_f32 v[44:45], v[34:35], v[172:173], v[44:45] op_sel_hi:[0,1,1]
	v_pk_fma_f32 v[30:31], v[34:35], v[30:31], v[40:41] op_sel_hi:[0,1,1]
	v_pk_fma_f32 v[46:47], v[34:35], v[174:175], v[46:47] op_sel_hi:[0,1,1]
	v_pk_fma_f32 v[32:33], v[34:35], v[32:33], v[42:43] op_sel_hi:[0,1,1]
	v_pk_fma_f32 v[16:17], v[34:35], v[26:27], v[16:17] op_sel_hi:[0,1,1]
	v_mov_b32_e32 v26, v45
	v_mov_b32_e32 v27, v31
	v_pk_fma_f32 v[18:19], v[34:35], v[186:187], v[0:1] op_sel_hi:[0,1,1]
	v_pk_fma_f32 v[14:15], v[34:35], v[28:29], v[14:15] op_sel_hi:[0,1,1]
	v_pk_fma_f32 v[0:1], v[34:35], v[140:141], v[2:3] op_sel_hi:[0,1,1]
	v_pk_fma_f32 v[2:3], v[34:35], v[138:139], v[12:13] op_sel_hi:[0,1,1]
	v_mov_b32_e32 v12, v44
	v_mov_b32_e32 v13, v30
	v_pk_mul_f32 v[26:27], v[26:27], v[26:27]
	v_mov_b32_e32 v28, v47
	v_mov_b32_e32 v29, v33
	v_pk_fma_f32 v[12:13], v[12:13], v[12:13], v[26:27]
	v_mov_b32_e32 v26, v46
	v_mov_b32_e32 v27, v32
	v_pk_mul_f32 v[28:29], v[28:29], v[28:29]
	v_pk_fma_f32 v[22:23], v[34:35], v[178:179], v[38:39] op_sel_hi:[0,1,1]
	v_pk_fma_f32 v[24:25], v[34:35], v[176:177], v[36:37] op_sel_hi:[0,1,1]
	v_pk_fma_f32 v[26:27], v[26:27], v[26:27], v[28:29]
	v_pk_mul_f32 v[28:29], v[24:25], v[24:25]
	v_pk_add_f32 v[12:13], v[12:13], v[26:27]
	v_pk_mul_f32 v[26:27], v[22:23], v[22:23]
	v_pk_fma_f32 v[20:21], v[34:35], v[184:185], v[102:103] op_sel_hi:[0,1,1]
	v_pk_fma_f32 v[8:9], v[34:35], v[144:145], v[8:9] op_sel_hi:[0,1,1]
; DI unsigned pk2(float lo, float hi) { return pg8::cvt_pk_bf16(lo, hi); }
; DI float fexp2(float x) { return __builtin_amdgcn_exp2f(x); }
; DI f32x4 bf4(v2u raw) { return (f32x4){bf2f((unsigned short)(raw.x & 0xffffu)), bf2f((unsigned short)(raw.x >> 16)), bf2f((unsigned short)(raw.y & 0xffffu)), bf2f((unsigned short)(raw.y >> 16))}; }
; DI void ret_out_phase(const Params& P, LAS unsigned char* lds, int r, const bf16* QKV, const bf16* ST, bf16* CAT) {
;     ...
;         float ss = 0.f;
; #pragma unroll
;         for (int t = 0; t < 8; ++t) ss += (yacc[t][0] * yacc[t][0] + yacc[t][1] * yacc[t][1]) + (yacc[t][2] * yacc[t][2] + yacc[t][3] * yacc[t][3]);
;         ss += __shfl_xor(ss, 16); ss += __shfl_xor(ss, 32);
;         const float rstd = 1.0f / sqrtf(ss * (1.0f / 128.0f) + EPS);
; #pragma unroll
;         for (int t = 0; t < 8; ++t) { const f32x4 gt = bf4(gtv[t]); f32x4 o;
; #pragma unroll
;             for (int i = 0; i < 4; ++i) o[i] = gt[i] * __builtin_amdgcn_rcpf(1.0f + fexp2(-gt[i] * LOG2E)) * yacc[t][i] * rstd;
;             v2u w; w.x = pk2(o[0], o[1]); w.y = pk2(o[2], o[3]);
;             *(v2u*)(CAT + tok * D + h * 128 + 16 * t + 4 * g) = w; }
	v_pk_fma_f32 v[10:11], v[34:35], v[142:143], v[10:11] op_sel_hi:[0,1,1]
	v_pk_fma_f32 v[4:5], v[34:35], v[148:149], v[4:5] op_sel_hi:[0,1,1]
	v_pk_fma_f32 v[6:7], v[34:35], v[146:147], v[6:7] op_sel_hi:[0,1,1]
	v_pk_mov_b32 v[34:35], v[28:29], v[26:27] op_sel:[1,0]
	v_mov_b32_e32 v29, v27
	v_pk_add_f32 v[26:27], v[34:35], v[28:29]
	v_mul_f32_e32 v28, v16, v16
	v_mul_f32_e32 v29, v17, v17
	v_pk_add_f32 v[12:13], v[12:13], v[12:13] op_sel:[0,1] op_sel_hi:[1,0]
	v_pk_add_f32 v[26:27], v[26:27], v[26:27] op_sel:[0,1] op_sel_hi:[1,0]
	v_mov_b32_e32 v13, v28
	v_mov_b32_e32 v27, v29
	v_pk_add_f32 v[12:13], v[12:13], v[26:27]
	v_mul_f32_e32 v26, v21, v21
	v_mul_f32_e32 v28, v19, v19
	v_mul_f32_e32 v34, v14, v14
	v_mul_f32_e32 v35, v15, v15
	v_pk_fma_f32 v[26:27], v[20:21], v[20:21], v[26:27] op_sel_hi:[1,1,0]
	v_pk_fma_f32 v[28:29], v[18:19], v[18:19], v[28:29] op_sel_hi:[1,1,0]
	v_mov_b32_e32 v27, v34
	v_mov_b32_e32 v29, v35
	v_pk_add_f32 v[26:27], v[26:27], v[28:29]
	v_pk_mul_f32 v[28:29], v[10:11], v[10:11]
	v_pk_add_f32 v[12:13], v[12:13], v[26:27]
	v_pk_mul_f32 v[26:27], v[8:9], v[8:9]
	v_pk_add_f32 v[12:13], v[12:13], v[12:13] op_sel:[0,1] op_sel_hi:[1,0]
	v_pk_mov_b32 v[34:35], v[28:29], v[26:27] op_sel:[1,0]
	v_mov_b32_e32 v29, v27
	v_pk_add_f32 v[26:27], v[34:35], v[28:29]
	v_mul_f32_e32 v28, v2, v2
	v_mul_f32_e32 v29, v3, v3
	v_pk_add_f32 v[26:27], v[26:27], v[26:27] op_sel:[0,1] op_sel_hi:[1,0]
	v_mov_b32_e32 v13, v28
	v_mov_b32_e32 v27, v29
	v_pk_add_f32 v[12:13], v[12:13], v[26:27]
	v_mul_f32_e32 v26, v7, v7
	v_mul_f32_e32 v28, v5, v5
	v_mul_f32_e32 v34, v0, v0
	v_mul_f32_e32 v35, v1, v1
	v_pk_fma_f32 v[26:27], v[6:7], v[6:7], v[26:27] op_sel_hi:[1,1,0]
	v_pk_fma_f32 v[28:29], v[4:5], v[4:5], v[28:29] op_sel_hi:[1,1,0]
	v_mov_b32_e32 v27, v34
	v_mov_b32_e32 v29, v35
	v_pk_add_f32 v[26:27], v[26:27], v[28:29]
	v_lshlrev_b32_e32 v34, 16, v101
	v_pk_add_f32 v[12:13], v[12:13], v[26:27]
	v_and_b32_e32 v36, 0xffff0000, v101
	v_add_f32_e32 v12, v12, v13
	v_cndmask_b32_e32 v13, v156, v163, vcc
	v_lshlrev_b32_e32 v13, 2, v13
	ds_bpermute_b32 v13, v13, v12
	v_cmp_lt_i32_e32 vcc, v164, v158
	s_waitcnt lgkmcnt(0)
	v_add_f32_e32 v12, v12, v13
	v_cndmask_b32_e32 v13, v156, v164, vcc
	v_lshlrev_b32_e32 v13, 2, v13
	ds_bpermute_b32 v13, v13, v12
	s_waitcnt lgkmcnt(0)
	v_add_f32_e32 v12, v12, v13
	v_fmamk_f32 v12, v12, 0x3c000000, v153
	v_mul_f32_e32 v13, 0x4f800000, v12
	v_cmp_gt_f32_e32 vcc, s24, v12
	s_nop 1
	v_cndmask_b32_e32 v12, v12, v13, vcc
	v_sqrt_f32_e32 v13, v12
	s_nop 0
	v_add_u32_e32 v26, -1, v13
	v_fma_f32 v27, -v26, v13, v12
	v_cmp_ge_f32_e64 s[4:5], 0, v27
	v_add_u32_e32 v27, 1, v13
	s_nop 0
	v_cndmask_b32_e64 v26, v13, v26, s[4:5]
	v_fma_f32 v13, -v27, v13, v12
	v_cmp_lt_f32_e64 s[4:5], 0, v13
	s_nop 1
	v_cndmask_b32_e64 v13, v26, v27, s[4:5]
	v_mul_f32_e32 v26, 0x37800000, v13
	v_cndmask_b32_e32 v13, v13, v26, vcc
	v_cmp_class_f32_e32 vcc, v12, v154
	s_nop 1
	v_cndmask_b32_e32 v12, v13, v12, vcc
	v_div_scale_f32 v13, s[0:1], v12, v12, 1.0
	v_rcp_f32_e32 v26, v13
	s_mov_b32 s0, s42
	v_fma_f32 v27, -v13, v26, 1.0
	v_fmac_f32_e32 v26, v27, v26
	v_div_scale_f32 v27, vcc, 1.0, v12, 1.0
	v_mul_f32_e32 v28, v27, v26
	v_fma_f32 v29, -v13, v28, v27
	v_fmac_f32_e32 v28, v29, v26
	v_fma_f32 v13, -v13, v28, v27
	v_div_fmas_f32 v13, v13, v26, v28
	v_lshlrev_b32_e32 v26, 16, v100
	v_and_b32_e32 v27, 0xffff0000, v100
	v_mul_f32_e32 v29, 0xbfb8aa3b, v26
	v_mul_f32_e32 v35, 0xbfb8aa3b, v27
	v_exp_f32_e32 v29, v29
	v_exp_f32_e32 v35, v35
	v_div_fixup_f32 v28, v13, v12, 1.0
	v_lshlrev_b64 v[12:13], 12, v[84:85]
	v_add_f32_e32 v29, 1.0, v29
	v_add_f32_e32 v35, 1.0, v35
	v_rcp_f32_e32 v29, v29
	v_rcp_f32_e32 v35, v35
	v_lshl_add_u64 v[12:13], s[30:31], 0, v[12:13]
	v_lshl_add_u64 v[12:13], v[12:13], 0, s[6:7]
	v_mul_f32_e32 v26, v29, v26
	v_mul_f32_e32 v27, v35, v27
	v_mul_f32_e32 v29, 0xbfb8aa3b, v34
	v_mul_f32_e32 v35, 0xbfb8aa3b, v36
	v_exp_f32_e32 v29, v29
	v_exp_f32_e32 v35, v35
	v_mul_f32_e32 v26, v26, v44
	v_mul_f32_e32 v26, v26, v28
	v_add_f32_e32 v29, 1.0, v29
	v_add_f32_e32 v35, 1.0, v35
	v_rcp_f32_e32 v29, v29
	v_rcp_f32_e32 v35, v35
	v_mul_f32_e32 v27, v27, v45
	v_lshl_add_u64 v[12:13], v[12:13], 0, v[82:83]
	v_mul_f32_e32 v29, v29, v34
	v_mul_f32_e32 v34, v35, v36
	v_mul_f32_e32 v27, v27, v28
	v_mul_f32_e32 v29, v29, v46
	v_mul_f32_e32 v34, v34, v47
	v_cvt_pk_bf16_f32 v224, v26, v27
	v_mul_f32_e32 v29, v29, v28
	v_mul_f32_e32 v34, v34, v28
	v_cvt_pk_bf16_f32 v225, v29, v34
	v_lshlrev_b32_e32 v26, 16, v98
	v_mul_f32_e32 v29, 0xbfb8aa3b, v26
	v_exp_f32_e32 v29, v29
	v_and_b32_e32 v27, 0xffff0000, v98
	v_lshlrev_b32_e32 v34, 16, v99
	v_mul_f32_e32 v35, 0xbfb8aa3b, v27
	v_add_f32_e32 v29, 1.0, v29
	v_rcp_f32_e32 v29, v29
	v_and_b32_e32 v36, 0xffff0000, v99
	v_exp_f32_e32 v35, v35
	v_mul_f32_e32 v26, v29, v26
	v_mul_f32_e32 v26, v26, v30
	v_mul_f32_e32 v29, 0xbfb8aa3b, v34
	v_mul_f32_e32 v30, 0xbfb8aa3b, v36
	v_exp_f32_e32 v29, v29
	v_exp_f32_e32 v30, v30
	v_add_f32_e32 v35, 1.0, v35
	v_rcp_f32_e32 v35, v35
	v_add_f32_e32 v29, 1.0, v29
	v_add_f32_e32 v30, 1.0, v30
	v_rcp_f32_e32 v29, v29
	v_rcp_f32_e32 v30, v30
	v_mul_f32_e32 v27, v35, v27
	v_mul_f32_e32 v26, v26, v28
	v_mul_f32_e32 v27, v27, v31
	v_mul_f32_e32 v29, v29, v34
	v_mul_f32_e32 v30, v30, v36
	v_mul_f32_e32 v27, v27, v28
	v_mul_f32_e32 v29, v29, v32
	v_mul_f32_e32 v30, v30, v33
	v_cvt_pk_bf16_f32 v226, v26, v27
	v_mul_f32_e32 v29, v29, v28
	v_mul_f32_e32 v30, v30, v28
	v_cvt_pk_bf16_f32 v227, v29, v30
	v_mbcnt_lo_u32_b32 v234, -1, 0
	v_mbcnt_hi_u32_b32 v234, -1, v234
	v_mov_b32_e32 v235, 0
	v_bfe_u32 v234, v234, 4, 1
	v_mul_u32_u24_e32 v234, 24, v234
	v_lshl_add_u64 v[232:233], v[12:13], 0, v[234:235]
; DI unsigned pk2(float lo, float hi) { return pg8::cvt_pk_bf16(lo, hi); }
; DI float fexp2(float x) { return __builtin_amdgcn_exp2f(x); }
; DI f32x4 bf4(v2u raw) { return (f32x4){bf2f((unsigned short)(raw.x & 0xffffu)), bf2f((unsigned short)(raw.x >> 16)), bf2f((unsigned short)(raw.y & 0xffffu)), bf2f((unsigned short)(raw.y >> 16))}; }
; DI void ret_out_phase(const Params& P, LAS unsigned char* lds, int r, const bf16* QKV, const bf16* ST, bf16* CAT) {
;     ...
; #pragma unroll
;         for (int t = 0; t < 8; ++t) { const f32x4 gt = bf4(gtv[t]); f32x4 o;
; #pragma unroll
;             for (int i = 0; i < 4; ++i) o[i] = gt[i] * __builtin_amdgcn_rcpf(1.0f + fexp2(-gt[i] * LOG2E)) * yacc[t][i] * rstd;
;             v2u w; w.x = pk2(o[0], o[1]); w.y = pk2(o[2], o[3]);
;             *(v2u*)(CAT + tok * D + h * 128 + 16 * t + 4 * g) = w; }
;         __syncthreads();
	s_nop 1
	v_permlane16_swap_b32_e32 v224, v226
	v_permlane16_swap_b32_e32 v225, v227
	global_store_dwordx4 v[232:233], v[224:227], off
	v_lshlrev_b32_e32 v26, 16, v96
	v_and_b32_e32 v27, 0xffff0000, v96
	v_mul_f32_e32 v29, 0xbfb8aa3b, v26
	v_exp_f32_e32 v29, v29
	v_mul_f32_e32 v31, 0xbfb8aa3b, v27
	v_exp_f32_e32 v31, v31
	v_lshlrev_b32_e32 v30, 16, v97
	v_add_f32_e32 v29, 1.0, v29
	v_rcp_f32_e32 v29, v29
	v_add_f32_e32 v31, 1.0, v31
	v_rcp_f32_e32 v31, v31
	v_and_b32_e32 v32, 0xffff0000, v97
	v_mul_f32_e32 v26, v29, v26
	v_mul_f32_e32 v24, v26, v24
	v_mul_f32_e32 v26, v31, v27
	v_mul_f32_e32 v27, 0xbfb8aa3b, v30
	v_exp_f32_e32 v27, v27
	v_mul_f32_e32 v25, v26, v25
	v_mul_f32_e32 v26, 0xbfb8aa3b, v32
	v_exp_f32_e32 v26, v26
	v_add_f32_e32 v27, 1.0, v27
	v_rcp_f32_e32 v27, v27
	v_mul_f32_e32 v24, v24, v28
	v_add_f32_e32 v26, 1.0, v26
	v_rcp_f32_e32 v26, v26
	v_mul_f32_e32 v27, v27, v30
	v_mul_f32_e32 v22, v27, v22
	v_mul_f32_e32 v27, v22, v28
	v_mul_f32_e32 v22, v26, v32
	v_mul_f32_e32 v22, v22, v23
	v_mul_f32_e32 v25, v25, v28
	v_mul_f32_e32 v23, v22, v28
	v_cvt_pk_bf16_f32 v228, v24, v25
	v_cvt_pk_bf16_f32 v229, v27, v23
	v_lshlrev_b32_e32 v22, 16, v94
	v_and_b32_e32 v23, 0xffff0000, v94
	v_mul_f32_e32 v24, 0xbfb8aa3b, v22
	v_exp_f32_e32 v24, v24
	v_mul_f32_e32 v26, 0xbfb8aa3b, v23
	v_exp_f32_e32 v26, v26
	v_lshlrev_b32_e32 v25, 16, v95
	v_add_f32_e32 v24, 1.0, v24
	v_rcp_f32_e32 v24, v24
	v_add_f32_e32 v26, 1.0, v26
	v_rcp_f32_e32 v26, v26
	v_and_b32_e32 v27, 0xffff0000, v95
	v_mul_f32_e32 v22, v24, v22
	v_mul_f32_e32 v20, v22, v20
	v_mul_f32_e32 v22, v26, v23
	v_mul_f32_e32 v23, 0xbfb8aa3b, v25
	v_exp_f32_e32 v23, v23
	v_mul_f32_e32 v21, v22, v21
	v_mul_f32_e32 v22, 0xbfb8aa3b, v27
	v_exp_f32_e32 v22, v22
	v_add_f32_e32 v23, 1.0, v23
	v_rcp_f32_e32 v23, v23
	v_mul_f32_e32 v20, v20, v28
	v_add_f32_e32 v22, 1.0, v22
	v_rcp_f32_e32 v22, v22
	v_mul_f32_e32 v23, v23, v25
	v_mul_f32_e32 v18, v23, v18
	v_mul_f32_e32 v23, v18, v28
	v_mul_f32_e32 v18, v22, v27
	v_mul_f32_e32 v18, v18, v19
	v_mul_f32_e32 v21, v21, v28
	v_mul_f32_e32 v19, v18, v28
	v_cvt_pk_bf16_f32 v230, v20, v21
	v_cvt_pk_bf16_f32 v231, v23, v19
	s_nop 1
	v_permlane16_swap_b32_e32 v228, v230
	v_permlane16_swap_b32_e32 v229, v231
	global_store_dwordx4 v[232:233], v[228:231], off offset:64
	v_lshlrev_b32_e32 v18, 16, v92
	v_and_b32_e32 v19, 0xffff0000, v92
	v_mul_f32_e32 v20, 0xbfb8aa3b, v18
	v_exp_f32_e32 v20, v20
	v_mul_f32_e32 v22, 0xbfb8aa3b, v19
	v_exp_f32_e32 v22, v22
	v_lshlrev_b32_e32 v21, 16, v93
	v_add_f32_e32 v20, 1.0, v20
	v_rcp_f32_e32 v20, v20
	v_add_f32_e32 v22, 1.0, v22
	v_rcp_f32_e32 v22, v22
	v_and_b32_e32 v23, 0xffff0000, v93
	v_mul_f32_e32 v18, v20, v18
	v_mul_f32_e32 v16, v18, v16
	v_mul_f32_e32 v18, v22, v19
	v_mul_f32_e32 v19, 0xbfb8aa3b, v21
	v_exp_f32_e32 v19, v19
	v_mul_f32_e32 v17, v18, v17
	v_mul_f32_e32 v18, 0xbfb8aa3b, v23
	v_exp_f32_e32 v18, v18
	v_add_f32_e32 v19, 1.0, v19
	v_rcp_f32_e32 v19, v19
	v_mul_f32_e32 v16, v16, v28
	v_add_f32_e32 v18, 1.0, v18
	v_rcp_f32_e32 v18, v18
	v_mul_f32_e32 v19, v19, v21
	v_mul_f32_e32 v14, v19, v14
	v_mul_f32_e32 v19, v14, v28
	v_mul_f32_e32 v14, v18, v23
	v_mul_f32_e32 v14, v14, v15
	v_mul_f32_e32 v17, v17, v28
	v_mul_f32_e32 v15, v14, v28
	v_cvt_pk_bf16_f32 v224, v16, v17
	v_cvt_pk_bf16_f32 v225, v19, v15
	v_lshlrev_b32_e32 v14, 16, v90
	v_and_b32_e32 v15, 0xffff0000, v90
	v_mul_f32_e32 v16, 0xbfb8aa3b, v14
	v_exp_f32_e32 v16, v16
	v_mul_f32_e32 v18, 0xbfb8aa3b, v15
	v_exp_f32_e32 v18, v18
	v_lshlrev_b32_e32 v17, 16, v91
	v_add_f32_e32 v16, 1.0, v16
	v_rcp_f32_e32 v16, v16
	v_add_f32_e32 v18, 1.0, v18
	v_rcp_f32_e32 v18, v18
	v_and_b32_e32 v19, 0xffff0000, v91
	v_mul_f32_e32 v14, v16, v14
	v_mul_f32_e32 v10, v14, v10
	v_mul_f32_e32 v14, v18, v15
	v_mul_f32_e32 v15, 0xbfb8aa3b, v17
	v_exp_f32_e32 v15, v15
	v_mul_f32_e32 v11, v14, v11
	v_mul_f32_e32 v14, 0xbfb8aa3b, v19
	v_exp_f32_e32 v14, v14
	v_add_f32_e32 v15, 1.0, v15
	v_rcp_f32_e32 v15, v15
	v_mul_f32_e32 v10, v10, v28
	v_add_f32_e32 v14, 1.0, v14
	v_rcp_f32_e32 v14, v14
	v_mul_f32_e32 v15, v15, v17
	v_mul_f32_e32 v8, v15, v8
	v_mul_f32_e32 v15, v8, v28
	v_mul_f32_e32 v8, v14, v19
	v_mul_f32_e32 v8, v8, v9
	v_mul_f32_e32 v11, v11, v28
	v_mul_f32_e32 v9, v8, v28
	v_cvt_pk_bf16_f32 v226, v10, v11
	v_cvt_pk_bf16_f32 v227, v15, v9
	s_nop 1
	v_permlane16_swap_b32_e32 v224, v226
	v_permlane16_swap_b32_e32 v225, v227
	global_store_dwordx4 v[232:233], v[224:227], off offset:128
	v_lshlrev_b32_e32 v8, 16, v88
	v_and_b32_e32 v9, 0xffff0000, v88
	v_mul_f32_e32 v10, 0xbfb8aa3b, v8
	v_exp_f32_e32 v10, v10
	v_mul_f32_e32 v14, 0xbfb8aa3b, v9
	v_exp_f32_e32 v14, v14
	v_lshlrev_b32_e32 v11, 16, v89
	v_add_f32_e32 v10, 1.0, v10
	v_rcp_f32_e32 v10, v10
	v_add_f32_e32 v14, 1.0, v14
	v_rcp_f32_e32 v14, v14
	v_and_b32_e32 v15, 0xffff0000, v89
	v_mul_f32_e32 v8, v10, v8
	v_mul_f32_e32 v6, v8, v6
	v_mul_f32_e32 v8, v14, v9
	v_mul_f32_e32 v9, 0xbfb8aa3b, v11
	v_exp_f32_e32 v9, v9
	v_mul_f32_e32 v7, v8, v7
	v_mul_f32_e32 v8, 0xbfb8aa3b, v15
	v_exp_f32_e32 v8, v8
	v_add_f32_e32 v9, 1.0, v9
	v_rcp_f32_e32 v9, v9
	v_mul_f32_e32 v6, v6, v28
	v_add_f32_e32 v8, 1.0, v8
	v_rcp_f32_e32 v8, v8
	v_mul_f32_e32 v9, v9, v11
	v_mul_f32_e32 v4, v9, v4
	v_mul_f32_e32 v9, v4, v28
	v_mul_f32_e32 v4, v8, v15
	v_mul_f32_e32 v4, v4, v5
	v_mul_f32_e32 v7, v7, v28
	v_mul_f32_e32 v5, v4, v28
	v_cvt_pk_bf16_f32 v228, v6, v7
	v_cvt_pk_bf16_f32 v229, v9, v5
	v_lshlrev_b32_e32 v4, 16, v86
	v_and_b32_e32 v5, 0xffff0000, v86
	v_mul_f32_e32 v6, 0xbfb8aa3b, v4
	v_exp_f32_e32 v6, v6
	v_mul_f32_e32 v8, 0xbfb8aa3b, v5
	v_exp_f32_e32 v8, v8
	v_lshlrev_b32_e32 v7, 16, v87
	v_add_f32_e32 v6, 1.0, v6
	v_rcp_f32_e32 v6, v6
	v_add_f32_e32 v8, 1.0, v8
	v_rcp_f32_e32 v8, v8
	v_and_b32_e32 v9, 0xffff0000, v87
	v_mul_f32_e32 v4, v6, v4
	v_mul_f32_e32 v2, v4, v2
	v_mul_f32_e32 v4, v8, v5
	v_mul_f32_e32 v5, 0xbfb8aa3b, v7
	v_exp_f32_e32 v5, v5
	v_mul_f32_e32 v3, v4, v3
	v_mul_f32_e32 v4, 0xbfb8aa3b, v9
	v_exp_f32_e32 v4, v4
	v_add_f32_e32 v5, 1.0, v5
	v_rcp_f32_e32 v5, v5
	v_mul_f32_e32 v2, v2, v28
	v_add_f32_e32 v4, 1.0, v4
	v_rcp_f32_e32 v4, v4
	v_mul_f32_e32 v5, v5, v7
	v_mul_f32_e32 v0, v5, v0
	v_mul_f32_e32 v5, v0, v28
	v_mul_f32_e32 v0, v4, v9
	v_mul_f32_e32 v0, v0, v1
	v_mul_f32_e32 v1, v0, v28
	v_mul_f32_e32 v3, v3, v28
	v_cvt_pk_bf16_f32 v230, v2, v3
	v_cvt_pk_bf16_f32 v231, v5, v1
	s_nop 1
	v_permlane16_swap_b32_e32 v228, v230
	v_permlane16_swap_b32_e32 v229, v231
	global_store_dwordx4 v[232:233], v[228:231], off offset:192
	s_waitcnt lgkmcnt(0)
	s_barrier
	s_add_i32 s20, s0, s20
	s_cmpk_gt_i32 s20, 0x5ff
	s_cbranch_scc0 .LBB0_180

; DI unsigned pk2(float lo, float hi) { return pg8::cvt_pk_bf16(lo, hi); }
; DI void na_phase(const Params& P, LAS unsigned char* lds, int r, const bf16* QKV, bf16* CAT) {
;     ...
;         for (int tl = 0; tl < 2; ++tl) { float lt = lrun[tl]; lt += __shfl_xor(lt, 16); lt += __shfl_xor(lt, 32); const float inv = 1.0f / lt;
;             bf16* op = CAT + (size_t)((gr0 + qr) * 64 + (cbp + tl) * 16 + li) * D + h * 128 + 4 * g;
; #pragma unroll
;             for (int t = 0; t < 8; ++t) { v2u w; w.x = pk2(oacc[tl][t][0] * inv, oacc[tl][t][1] * inv); w.y = pk2(oacc[tl][t][2] * inv, oacc[tl][t][3] * inv); *(v2u*)(op + 16 * t) = w; } }
.LBB0_243:
	v_ashrrev_i32_e32 v119, 31, v118
	v_ashrrev_i32_e32 v117, 31, v116
	v_cmp_lt_i32_e32 vcc, v163, v158
	s_add_u32 s6, s16, s78
	s_addc_u32 s7, s17, s79
	v_cndmask_b32_e32 v0, v156, v163, vcc
	v_lshlrev_b32_e32 v6, 2, v0
	ds_bpermute_b32 v0, v6, v121
	v_cmp_lt_i32_e32 vcc, v164, v158
	ds_bpermute_b32 v6, v6, v140
	s_waitcnt lgkmcnt(0)
	v_add_f32_e32 v0, v121, v0
	v_cndmask_b32_e32 v1, v156, v164, vcc
	v_lshlrev_b32_e32 v7, 2, v1
	ds_bpermute_b32 v1, v7, v0
	v_ashrrev_i32_e32 v121, 31, v120
	s_waitcnt lgkmcnt(0)
	v_add_f32_e32 v2, v0, v1
	v_div_scale_f32 v3, s[8:9], v2, v2, 1.0
	v_rcp_f32_e32 v4, v3
	v_div_scale_f32 v5, vcc, 1.0, v2, 1.0
	v_lshl_add_u64 v[0:1], v[120:121], 1, s[6:7]
	v_fma_f32 v8, -v3, v4, 1.0
	v_fmac_f32_e32 v4, v8, v4
	v_mul_f32_e32 v8, v5, v4
	v_fma_f32 v9, -v3, v8, v5
	v_fmac_f32_e32 v8, v9, v4
	v_fma_f32 v3, -v3, v8, v5
	v_div_fmas_f32 v3, v3, v4, v8
	v_div_fixup_f32 v8, v3, v2, 1.0
	v_lshlrev_b64 v[2:3], 12, v[118:119]
	v_lshl_add_u64 v[2:3], v[0:1], 0, v[2:3]
	v_mbcnt_lo_u32_b32 v232, -1, 0
	v_mbcnt_hi_u32_b32 v232, -1, v232
	v_mov_b32_e32 v233, 0
	v_bfe_u32 v232, v232, 4, 1
	v_mul_u32_u24_e32 v232, 24, v232
	v_lshl_add_u64 v[234:235], v[2:3], 0, v[232:233]
	v_mul_f32_e32 v216, v108, v8
	v_mul_f32_e32 v217, v109, v8
	v_mul_f32_e32 v218, v110, v8
	v_mul_f32_e32 v219, v111, v8
	v_mul_f32_e32 v220, v104, v8
	v_mul_f32_e32 v221, v105, v8
	v_mul_f32_e32 v222, v106, v8
	v_mul_f32_e32 v223, v107, v8
	v_cvt_pk_bf16_f32 v224, v216, v217
	v_cvt_pk_bf16_f32 v225, v218, v219
	v_cvt_pk_bf16_f32 v226, v220, v221
	v_cvt_pk_bf16_f32 v227, v222, v223
	s_nop 1
	v_permlane16_swap_b32_e32 v224, v226
	v_permlane16_swap_b32_e32 v225, v227
	global_store_dwordx4 v[234:235], v[224:227], off
	v_mul_f32_e32 v216, v100, v8
	v_mul_f32_e32 v217, v101, v8
	v_mul_f32_e32 v218, v102, v8
	v_mul_f32_e32 v219, v103, v8
	v_mul_f32_e32 v220, v96, v8
	v_mul_f32_e32 v221, v97, v8
	v_mul_f32_e32 v222, v98, v8
	v_mul_f32_e32 v223, v99, v8
	v_cvt_pk_bf16_f32 v228, v216, v217
	v_cvt_pk_bf16_f32 v229, v218, v219
	v_cvt_pk_bf16_f32 v230, v220, v221
	v_cvt_pk_bf16_f32 v231, v222, v223
	s_nop 1
	v_permlane16_swap_b32_e32 v228, v230
	v_permlane16_swap_b32_e32 v229, v231
	global_store_dwordx4 v[234:235], v[228:231], off offset:64
	v_mul_f32_e32 v216, v92, v8
	v_mul_f32_e32 v217, v93, v8
	v_mul_f32_e32 v218, v94, v8
	v_mul_f32_e32 v219, v95, v8
	v_mul_f32_e32 v220, v88, v8
	v_mul_f32_e32 v221, v89, v8
	v_mul_f32_e32 v222, v90, v8
	v_mul_f32_e32 v223, v91, v8
	v_cvt_pk_bf16_f32 v224, v216, v217
	v_cvt_pk_bf16_f32 v225, v218, v219
	v_cvt_pk_bf16_f32 v226, v220, v221
	v_cvt_pk_bf16_f32 v227, v222, v223
	s_nop 1
	v_permlane16_swap_b32_e32 v224, v226
	v_permlane16_swap_b32_e32 v225, v227
	global_store_dwordx4 v[234:235], v[224:227], off offset:128
	v_mul_f32_e32 v216, v84, v8
	v_mul_f32_e32 v217, v85, v8
	v_mul_f32_e32 v218, v86, v8
	v_mul_f32_e32 v219, v87, v8
	v_mul_f32_e32 v220, v80, v8
	v_mul_f32_e32 v221, v81, v8
	v_mul_f32_e32 v222, v82, v8
	v_mul_f32_e32 v223, v83, v8
	v_cvt_pk_bf16_f32 v228, v216, v217
	v_cvt_pk_bf16_f32 v229, v218, v219
	v_cvt_pk_bf16_f32 v230, v220, v221
	v_cvt_pk_bf16_f32 v231, v222, v223
	s_nop 1
	v_permlane16_swap_b32_e32 v228, v230
	v_permlane16_swap_b32_e32 v229, v231
	global_store_dwordx4 v[234:235], v[228:231], off offset:192
	v_add_f32_e32 v5, v140, v6
	ds_bpermute_b32 v6, v7, v5
	s_waitcnt lgkmcnt(0)
	v_add_f32_e32 v6, v5, v6
	v_div_scale_f32 v9, s[6:7], v6, v6, 1.0
	v_rcp_f32_e32 v10, v9
	s_nop 0
	v_fma_f32 v2, -v9, v10, 1.0
	v_fmac_f32_e32 v10, v2, v10
	v_div_scale_f32 v2, vcc, 1.0, v6, 1.0
	v_mul_f32_e32 v3, v2, v10
	v_fma_f32 v4, -v9, v3, v2
	v_fmac_f32_e32 v3, v4, v10
	v_fma_f32 v2, -v9, v3, v2
	v_div_fmas_f32 v2, v2, v10, v3
	v_div_fixup_f32 v4, v2, v6, 1.0
	v_lshlrev_b64 v[2:3], 12, v[116:117]
	v_lshl_add_u64 v[0:1], v[0:1], 0, v[2:3]
	v_lshl_add_u64 v[236:237], v[0:1], 0, v[232:233]
	v_mul_f32_e32 v216, v76, v4
	v_mul_f32_e32 v217, v77, v4
	v_mul_f32_e32 v218, v78, v4
	v_mul_f32_e32 v219, v79, v4
	v_mul_f32_e32 v220, v72, v4
	v_mul_f32_e32 v221, v73, v4
	v_mul_f32_e32 v222, v74, v4
	v_mul_f32_e32 v223, v75, v4
	v_cvt_pk_bf16_f32 v224, v216, v217
	v_cvt_pk_bf16_f32 v225, v218, v219
	v_cvt_pk_bf16_f32 v226, v220, v221
	v_cvt_pk_bf16_f32 v227, v222, v223
	s_nop 1
	v_permlane16_swap_b32_e32 v224, v226
	v_permlane16_swap_b32_e32 v225, v227
	global_store_dwordx4 v[236:237], v[224:227], off
	v_mul_f32_e32 v216, v64, v4
	v_mul_f32_e32 v217, v65, v4
	v_mul_f32_e32 v218, v66, v4
	v_mul_f32_e32 v219, v67, v4
	v_mul_f32_e32 v220, v52, v4
	v_mul_f32_e32 v221, v53, v4
	v_mul_f32_e32 v222, v54, v4
	v_mul_f32_e32 v223, v55, v4
	v_cvt_pk_bf16_f32 v228, v216, v217
	v_cvt_pk_bf16_f32 v229, v218, v219
	v_cvt_pk_bf16_f32 v230, v220, v221
	v_cvt_pk_bf16_f32 v231, v222, v223
	s_nop 1
	v_permlane16_swap_b32_e32 v228, v230
	v_permlane16_swap_b32_e32 v229, v231
	global_store_dwordx4 v[236:237], v[228:231], off offset:64
	v_mul_f32_e32 v216, v48, v4
	v_mul_f32_e32 v217, v49, v4
	v_mul_f32_e32 v218, v50, v4
	v_mul_f32_e32 v219, v51, v4
	v_mul_f32_e32 v220, v40, v4
	v_mul_f32_e32 v221, v41, v4
	v_mul_f32_e32 v222, v42, v4
	v_mul_f32_e32 v223, v43, v4
	v_cvt_pk_bf16_f32 v224, v216, v217
	v_cvt_pk_bf16_f32 v225, v218, v219
	v_cvt_pk_bf16_f32 v226, v220, v221
	v_cvt_pk_bf16_f32 v227, v222, v223
	s_nop 1
	v_permlane16_swap_b32_e32 v224, v226
	v_permlane16_swap_b32_e32 v225, v227
	global_store_dwordx4 v[236:237], v[224:227], off offset:128
	v_mul_f32_e32 v216, v28, v4
	v_mul_f32_e32 v217, v29, v4
	v_mul_f32_e32 v218, v30, v4
	v_mul_f32_e32 v219, v31, v4
	v_mul_f32_e32 v220, v24, v4
	v_mul_f32_e32 v221, v25, v4
	v_mul_f32_e32 v222, v26, v4
	v_mul_f32_e32 v223, v27, v4
	v_cvt_pk_bf16_f32 v228, v216, v217
	v_cvt_pk_bf16_f32 v229, v218, v219
	v_cvt_pk_bf16_f32 v230, v220, v221
	v_cvt_pk_bf16_f32 v231, v222, v223
	s_nop 1
	v_permlane16_swap_b32_e32 v228, v230
	v_permlane16_swap_b32_e32 v229, v231
	global_store_dwordx4 v[236:237], v[228:231], off offset:192
	s_mov_b32 s6, s42
	s_add_i32 s0, s6, s0
	s_cmpk_gt_i32 s0, 0x2ff
	s_cbranch_scc0 .LBB0_224
